# stack: vstage + scan landing-register reads + score key reads with immediate offsets and dead 64-bit address adds removed (250 VALU per score item)
# speedup vs baseline: 1.0003x; 1.0003x over previous
; __device__ void ph_score(const P& p, int* lds) {
;     ...
;   for (int it = blockIdx.x; it < 528 * 8; it += gridDim.x) {
;     const int h = it & 7, tile = it >> 3;
;     const size_t tok = (size_t)tile * 64 + w * 16 + fr;
;     float tv[2][16];
; #pragma unroll
;     for (int half = 0; half < 2; ++half) {
;       const u16* Kb = (half ? p_K2b : p_K1b) + h * 128 * 128;
;       f32x4 sc[8];
; #pragma unroll
;       for (int mt = 0; mt < 8; ++mt) sc[mt] = f32x4{0.f, 0.f, 0.f, 0.f};
; #pragma unroll
;       for (int ks = 0; ks < 4; ++ks) {
;         bf16x8 qf = *(const bf16x8*)(Qb + tok * 2048 + h * 256 + half * 128 + ks * 32 + fq * 8);
.Lsc_keys_ok:
	v_and_b32_e32 v223, 15, v220
	v_bfe_u32 v224, v220, 4, 2
	v_mul_u32_u24_e32 v223, 0x110, v223
	v_lshl_add_u32 v223, v224, 4, v223
	v_add_u32_e32 v224, 0xa8d0, v223
	v_add_u32_e32 v223, 0x2000, v223
	s_ashr_i32 s10, s82, 3
	s_ashr_i32 s11, s10, 31
	s_lshl_b64 s[10:11], s[10:11], 6
	v_lshl_add_u64 v[44:45], s[10:11], 0, v[16:17]
	s_and_b32 s83, s82, 7
	v_lshlrev_b64 v[0:1], 12, v[44:45]
	v_lshl_add_u64 v[0:1], s[2:3], 0, v[0:1]
	s_lshl_b32 s70, s83, 9
	v_lshl_add_u64 v[0:1], v[0:1], 0, s[70:71]
	s_lshl_b32 s70, s83, 15
	v_lshl_add_u64 v[14:15], v[22:23], 0, s[70:71]

; __device__ __forceinline__ f32x4 mfma16(bf16x8 a, bf16x8 b, f32x4 c) { return __builtin_amdgcn_mfma_f32_16x16x32_bf16(a, b, c, 0, 0, 0); }
; __device__ void ph_score(const P& p, int* lds) {
;     ...
; #pragma unroll
;       for (int ks = 0; ks < 4; ++ks) {
;         bf16x8 qf = *(const bf16x8*)(Qb + tok * 2048 + h * 256 + half * 128 + ks * 32 + fq * 8);
; #pragma unroll
;         for (int mt = 0; mt < 8; ++mt) {
;           bf16x8 kf = *(const bf16x8*)(Kb + (mt * 16 + fr) * 128 + ks * 32 + fq * 8);
;           sc[mt] = mfma16(kf, qf, sc[mt]);
	v_lshl_add_u64 v[0:1], v[0:1], 0, v[26:27]


; __device__ void ph_score(const P& p, int* lds) {
;     ...
;         bf16x8 qf = *(const bf16x8*)(Qb + tok * 2048 + h * 256 + half * 128 + ks * 32 + fq * 8);
; #pragma unroll
;         for (int mt = 0; mt < 8; ++mt) {
;           bf16x8 kf = *(const bf16x8*)(Kb + (mt * 16 + fr) * 128 + ks * 32 + fq * 8);
	ds_read_b128 v[2:5], v223 offset:0
	global_load_dwordx4 v[6:9], v[0:1], off
	global_load_dword v218, v[0:1], off offset:128
	global_load_dword v219, v[0:1], off offset:256
	global_load_dword v225, v[0:1], off offset:384
	v_lshl_add_u64 v[194:195], v[14:15], 0, 64


; __device__ __forceinline__ f32x4 mfma16(bf16x8 a, bf16x8 b, f32x4 c) { return __builtin_amdgcn_mfma_f32_16x16x32_bf16(a, b, c, 0, 0, 0); }
; __device__ void ph_score(const P& p, int* lds) {
;     ...
;         bf16x8 qf = *(const bf16x8*)(Qb + tok * 2048 + h * 256 + half * 128 + ks * 32 + fq * 8);
; #pragma unroll
;         for (int mt = 0; mt < 8; ++mt) {
;           bf16x8 kf = *(const bf16x8*)(Kb + (mt * 16 + fr) * 128 + ks * 32 + fq * 8);
;           sc[mt] = mfma16(kf, qf, sc[mt]);
	ds_read_b128 v[10:13], v223 offset:4352


; __device__ __forceinline__ f32x4 mfma16(bf16x8 a, bf16x8 b, f32x4 c) { return __builtin_amdgcn_mfma_f32_16x16x32_bf16(a, b, c, 0, 0, 0); }
; __device__ void ph_score(const P& p, int* lds) {
;     ...
;         bf16x8 qf = *(const bf16x8*)(Qb + tok * 2048 + h * 256 + half * 128 + ks * 32 + fq * 8);
; #pragma unroll
;         for (int mt = 0; mt < 8; ++mt) {
;           bf16x8 kf = *(const bf16x8*)(Kb + (mt * 16 + fr) * 128 + ks * 32 + fq * 8);
;           sc[mt] = mfma16(kf, qf, sc[mt]);
	ds_read_b128 v[50:53], v223 offset:8704


; __device__ __forceinline__ f32x4 mfma16(bf16x8 a, bf16x8 b, f32x4 c) { return __builtin_amdgcn_mfma_f32_16x16x32_bf16(a, b, c, 0, 0, 0); }
; __device__ void ph_score(const P& p, int* lds) {
;     ...
;         bf16x8 qf = *(const bf16x8*)(Qb + tok * 2048 + h * 256 + half * 128 + ks * 32 + fq * 8);
; #pragma unroll
;         for (int mt = 0; mt < 8; ++mt) {
;           bf16x8 kf = *(const bf16x8*)(Kb + (mt * 16 + fr) * 128 + ks * 32 + fq * 8);
;           sc[mt] = mfma16(kf, qf, sc[mt]);
	ds_read_b128 v[154:157], v223 offset:13056
	s_nop 0
	global_load_dwordx4 v[158:161], v[0:1], off offset:64


; __device__ __forceinline__ f32x4 mfma16(bf16x8 a, bf16x8 b, f32x4 c) { return __builtin_amdgcn_mfma_f32_16x16x32_bf16(a, b, c, 0, 0, 0); }
; __device__ void ph_score(const P& p, int* lds) {
;     ...
;         bf16x8 qf = *(const bf16x8*)(Qb + tok * 2048 + h * 256 + half * 128 + ks * 32 + fq * 8);
; #pragma unroll
;         for (int mt = 0; mt < 8; ++mt) {
;           bf16x8 kf = *(const bf16x8*)(Kb + (mt * 16 + fr) * 128 + ks * 32 + fq * 8);
;           sc[mt] = mfma16(kf, qf, sc[mt]);
	ds_read_b128 v[162:165], v223 offset:64


; __device__ __forceinline__ f32x4 mfma16(bf16x8 a, bf16x8 b, f32x4 c) { return __builtin_amdgcn_mfma_f32_16x16x32_bf16(a, b, c, 0, 0, 0); }
; __device__ void ph_score(const P& p, int* lds) {
;     ...
;         bf16x8 qf = *(const bf16x8*)(Qb + tok * 2048 + h * 256 + half * 128 + ks * 32 + fq * 8);
; #pragma unroll
;         for (int mt = 0; mt < 8; ++mt) {
;           bf16x8 kf = *(const bf16x8*)(Kb + (mt * 16 + fr) * 128 + ks * 32 + fq * 8);
;           sc[mt] = mfma16(kf, qf, sc[mt]);
	ds_read_b128 v[166:169], v223 offset:17408


; __device__ __forceinline__ f32x4 mfma16(bf16x8 a, bf16x8 b, f32x4 c) { return __builtin_amdgcn_mfma_f32_16x16x32_bf16(a, b, c, 0, 0, 0); }
; __device__ void ph_score(const P& p, int* lds) {
;     ...
;         bf16x8 qf = *(const bf16x8*)(Qb + tok * 2048 + h * 256 + half * 128 + ks * 32 + fq * 8);
; #pragma unroll
;         for (int mt = 0; mt < 8; ++mt) {
;           bf16x8 kf = *(const bf16x8*)(Kb + (mt * 16 + fr) * 128 + ks * 32 + fq * 8);
;           sc[mt] = mfma16(kf, qf, sc[mt]);
	ds_read_b128 v[170:173], v223 offset:21760
	v_lshl_add_u64 v[202:203], v[14:15], 0, s[72:73]


; __device__ __forceinline__ f32x4 mfma16(bf16x8 a, bf16x8 b, f32x4 c) { return __builtin_amdgcn_mfma_f32_16x16x32_bf16(a, b, c, 0, 0, 0); }
; __device__ void ph_score(const P& p, int* lds) {
;     ...
;         bf16x8 qf = *(const bf16x8*)(Qb + tok * 2048 + h * 256 + half * 128 + ks * 32 + fq * 8);
; #pragma unroll
;         for (int mt = 0; mt < 8; ++mt) {
;           bf16x8 kf = *(const bf16x8*)(Kb + (mt * 16 + fr) * 128 + ks * 32 + fq * 8);
;           sc[mt] = mfma16(kf, qf, sc[mt]);
	ds_read_b128 v[174:177], v223 offset:26112


; __device__ __forceinline__ f32x4 mfma16(bf16x8 a, bf16x8 b, f32x4 c) { return __builtin_amdgcn_mfma_f32_16x16x32_bf16(a, b, c, 0, 0, 0); }
; __device__ void ph_score(const P& p, int* lds) {
;     ...
;         bf16x8 qf = *(const bf16x8*)(Qb + tok * 2048 + h * 256 + half * 128 + ks * 32 + fq * 8);
; #pragma unroll
;         for (int mt = 0; mt < 8; ++mt) {
;           bf16x8 kf = *(const bf16x8*)(Kb + (mt * 16 + fr) * 128 + ks * 32 + fq * 8);
;           sc[mt] = mfma16(kf, qf, sc[mt]);
	ds_read_b128 v[178:181], v223 offset:30464


; __device__ __forceinline__ f32x4 mfma16(bf16x8 a, bf16x8 b, f32x4 c) { return __builtin_amdgcn_mfma_f32_16x16x32_bf16(a, b, c, 0, 0, 0); }
; __device__ void ph_score(const P& p, int* lds) {
;     ...
;         bf16x8 qf = *(const bf16x8*)(Qb + tok * 2048 + h * 256 + half * 128 + ks * 32 + fq * 8);
; #pragma unroll
;         for (int mt = 0; mt < 8; ++mt) {
;           bf16x8 kf = *(const bf16x8*)(Kb + (mt * 16 + fr) * 128 + ks * 32 + fq * 8);
;           sc[mt] = mfma16(kf, qf, sc[mt]);
	ds_read_b128 v[182:185], v223 offset:4416
	v_lshl_add_u64 v[14:15], v[14:15], 0, s[76:77]


; __device__ __forceinline__ f32x4 mfma16(bf16x8 a, bf16x8 b, f32x4 c) { return __builtin_amdgcn_mfma_f32_16x16x32_bf16(a, b, c, 0, 0, 0); }
; __device__ void ph_score(const P& p, int* lds) {
;     ...
;         bf16x8 qf = *(const bf16x8*)(Qb + tok * 2048 + h * 256 + half * 128 + ks * 32 + fq * 8);
; #pragma unroll
;         for (int mt = 0; mt < 8; ++mt) {
;           bf16x8 kf = *(const bf16x8*)(Kb + (mt * 16 + fr) * 128 + ks * 32 + fq * 8);
;           sc[mt] = mfma16(kf, qf, sc[mt]);
	ds_read_b128 v[186:189], v223 offset:8768
	s_waitcnt vmcnt(0) lgkmcnt(0)
	v_mfma_f32_16x16x32_bf16 v[2:5], v[2:5], v[6:9], 0


; __device__ __forceinline__ f32x4 mfma16(bf16x8 a, bf16x8 b, f32x4 c) { return __builtin_amdgcn_mfma_f32_16x16x32_bf16(a, b, c, 0, 0, 0); }
; __device__ void ph_score(const P& p, int* lds) {
;     ...
;         bf16x8 qf = *(const bf16x8*)(Qb + tok * 2048 + h * 256 + half * 128 + ks * 32 + fq * 8);
; #pragma unroll
;         for (int mt = 0; mt < 8; ++mt) {
;           bf16x8 kf = *(const bf16x8*)(Kb + (mt * 16 + fr) * 128 + ks * 32 + fq * 8);
;           sc[mt] = mfma16(kf, qf, sc[mt]);
	ds_read_b128 v[190:193], v223 offset:13120
	v_mfma_f32_16x16x32_bf16 v[10:13], v[10:13], v[6:9], 0
	v_mfma_f32_16x16x32_bf16 v[50:53], v[50:53], v[6:9], 0
	v_mfma_f32_16x16x32_bf16 v[154:157], v[154:157], v[6:9], 0
	v_mfma_f32_16x16x32_bf16 v[166:169], v[166:169], v[6:9], 0
	v_mfma_f32_16x16x32_bf16 v[170:173], v[170:173], v[6:9], 0
	v_mfma_f32_16x16x32_bf16 v[174:177], v[174:177], v[6:9], 0
	v_mfma_f32_16x16x32_bf16 v[6:9], v[178:181], v[6:9], 0


; __device__ __forceinline__ f32x4 mfma16(bf16x8 a, bf16x8 b, f32x4 c) { return __builtin_amdgcn_mfma_f32_16x16x32_bf16(a, b, c, 0, 0, 0); }
; __device__ void ph_score(const P& p, int* lds) {
;     ...
;         bf16x8 qf = *(const bf16x8*)(Qb + tok * 2048 + h * 256 + half * 128 + ks * 32 + fq * 8);
; #pragma unroll
;         for (int mt = 0; mt < 8; ++mt) {
;           bf16x8 kf = *(const bf16x8*)(Kb + (mt * 16 + fr) * 128 + ks * 32 + fq * 8);
;           sc[mt] = mfma16(kf, qf, sc[mt]);
	ds_read_b128 v[178:181], v223 offset:17472

; __device__ __forceinline__ f32x4 mfma16(bf16x8 a, bf16x8 b, f32x4 c) { return __builtin_amdgcn_mfma_f32_16x16x32_bf16(a, b, c, 0, 0, 0); }
; __device__ void ph_score(const P& p, int* lds) {
;     ...
;         bf16x8 qf = *(const bf16x8*)(Qb + tok * 2048 + h * 256 + half * 128 + ks * 32 + fq * 8);
; #pragma unroll
;         for (int mt = 0; mt < 8; ++mt) {
;           bf16x8 kf = *(const bf16x8*)(Kb + (mt * 16 + fr) * 128 + ks * 32 + fq * 8);
;           sc[mt] = mfma16(kf, qf, sc[mt]);
	v_mfma_f32_16x16x32_bf16 v[2:5], v[162:165], v[158:161], v[2:5]


; __device__ __forceinline__ f32x4 mfma16(bf16x8 a, bf16x8 b, f32x4 c) { return __builtin_amdgcn_mfma_f32_16x16x32_bf16(a, b, c, 0, 0, 0); }
; __device__ void ph_score(const P& p, int* lds) {
;     ...
;         bf16x8 qf = *(const bf16x8*)(Qb + tok * 2048 + h * 256 + half * 128 + ks * 32 + fq * 8);
; #pragma unroll
;         for (int mt = 0; mt < 8; ++mt) {
;           bf16x8 kf = *(const bf16x8*)(Kb + (mt * 16 + fr) * 128 + ks * 32 + fq * 8);
;           sc[mt] = mfma16(kf, qf, sc[mt]);
	ds_read_b128 v[162:165], v223 offset:21824


; __device__ __forceinline__ f32x4 mfma16(bf16x8 a, bf16x8 b, f32x4 c) { return __builtin_amdgcn_mfma_f32_16x16x32_bf16(a, b, c, 0, 0, 0); }
; __device__ void ph_score(const P& p, int* lds) {
;     ...
;         bf16x8 qf = *(const bf16x8*)(Qb + tok * 2048 + h * 256 + half * 128 + ks * 32 + fq * 8);
; #pragma unroll
;         for (int mt = 0; mt < 8; ++mt) {
;           bf16x8 kf = *(const bf16x8*)(Kb + (mt * 16 + fr) * 128 + ks * 32 + fq * 8);
;           sc[mt] = mfma16(kf, qf, sc[mt]);
	v_mfma_f32_16x16x32_bf16 v[10:13], v[182:185], v[158:161], v[10:13]


; __device__ __forceinline__ f32x4 mfma16(bf16x8 a, bf16x8 b, f32x4 c) { return __builtin_amdgcn_mfma_f32_16x16x32_bf16(a, b, c, 0, 0, 0); }
; __device__ void ph_score(const P& p, int* lds) {
;     ...
;         bf16x8 qf = *(const bf16x8*)(Qb + tok * 2048 + h * 256 + half * 128 + ks * 32 + fq * 8);
; #pragma unroll
;         for (int mt = 0; mt < 8; ++mt) {
;           bf16x8 kf = *(const bf16x8*)(Kb + (mt * 16 + fr) * 128 + ks * 32 + fq * 8);
;           sc[mt] = mfma16(kf, qf, sc[mt]);
	ds_read_b128 v[182:185], v223 offset:26176
	v_mfma_f32_16x16x32_bf16 v[50:53], v[186:189], v[158:161], v[50:53]


; __device__ __forceinline__ f32x4 mfma16(bf16x8 a, bf16x8 b, f32x4 c) { return __builtin_amdgcn_mfma_f32_16x16x32_bf16(a, b, c, 0, 0, 0); }
; __device__ void ph_score(const P& p, int* lds) {
;     ...
;         bf16x8 qf = *(const bf16x8*)(Qb + tok * 2048 + h * 256 + half * 128 + ks * 32 + fq * 8);
; #pragma unroll
;         for (int mt = 0; mt < 8; ++mt) {
;           bf16x8 kf = *(const bf16x8*)(Kb + (mt * 16 + fr) * 128 + ks * 32 + fq * 8);
;           sc[mt] = mfma16(kf, qf, sc[mt]);
	ds_read_b128 v[186:189], v223 offset:30528
	s_nop 0


; __device__ __forceinline__ f32x4 mfma16(bf16x8 a, bf16x8 b, f32x4 c) { return __builtin_amdgcn_mfma_f32_16x16x32_bf16(a, b, c, 0, 0, 0); }
; __device__ void ph_score(const P& p, int* lds) {
;     ...
;         bf16x8 qf = *(const bf16x8*)(Qb + tok * 2048 + h * 256 + half * 128 + ks * 32 + fq * 8);
; #pragma unroll
;         for (int mt = 0; mt < 8; ++mt) {
;           bf16x8 kf = *(const bf16x8*)(Kb + (mt * 16 + fr) * 128 + ks * 32 + fq * 8);
;           sc[mt] = mfma16(kf, qf, sc[mt]);
	ds_read_b128 v[194:197], v223 offset:128
	s_waitcnt vmcnt(0) lgkmcnt(0)
	v_mfma_f32_16x16x32_bf16 v[154:157], v[190:193], v[158:161], v[154:157]
	global_load_dwordx4 v[190:193], v[0:1], off offset:128
	v_mfma_f32_16x16x32_bf16 v[166:169], v[178:181], v[158:161], v[166:169]


; __device__ __forceinline__ f32x4 mfma16(bf16x8 a, bf16x8 b, f32x4 c) { return __builtin_amdgcn_mfma_f32_16x16x32_bf16(a, b, c, 0, 0, 0); }
; __device__ void ph_score(const P& p, int* lds) {
;     ...
;       for (int ks = 0; ks < 4; ++ks) {
;         bf16x8 qf = *(const bf16x8*)(Qb + tok * 2048 + h * 256 + half * 128 + ks * 32 + fq * 8);
; #pragma unroll
;         for (int mt = 0; mt < 8; ++mt) {
;           bf16x8 kf = *(const bf16x8*)(Kb + (mt * 16 + fr) * 128 + ks * 32 + fq * 8);
;           sc[mt] = mfma16(kf, qf, sc[mt]);
;         }
;       }
	ds_read_b128 v[178:181], v223 offset:4480

; __device__ __forceinline__ f32x4 mfma16(bf16x8 a, bf16x8 b, f32x4 c) { return __builtin_amdgcn_mfma_f32_16x16x32_bf16(a, b, c, 0, 0, 0); }
; __device__ void ph_score(const P& p, int* lds) {
;     ...
;       for (int ks = 0; ks < 4; ++ks) {
;         bf16x8 qf = *(const bf16x8*)(Qb + tok * 2048 + h * 256 + half * 128 + ks * 32 + fq * 8);
; #pragma unroll
;         for (int mt = 0; mt < 8; ++mt) {
;           bf16x8 kf = *(const bf16x8*)(Kb + (mt * 16 + fr) * 128 + ks * 32 + fq * 8);
;           sc[mt] = mfma16(kf, qf, sc[mt]);
;         }
;       }
	v_mfma_f32_16x16x32_bf16 v[162:165], v[162:165], v[158:161], v[170:173]
	s_nop 2


; __device__ __forceinline__ f32x4 mfma16(bf16x8 a, bf16x8 b, f32x4 c) { return __builtin_amdgcn_mfma_f32_16x16x32_bf16(a, b, c, 0, 0, 0); }
; __device__ void ph_score(const P& p, int* lds) {
;     ...
;       for (int ks = 0; ks < 4; ++ks) {
;         bf16x8 qf = *(const bf16x8*)(Qb + tok * 2048 + h * 256 + half * 128 + ks * 32 + fq * 8);
; #pragma unroll
;         for (int mt = 0; mt < 8; ++mt) {
;           bf16x8 kf = *(const bf16x8*)(Kb + (mt * 16 + fr) * 128 + ks * 32 + fq * 8);
;           sc[mt] = mfma16(kf, qf, sc[mt]);
;         }
;       }
	ds_read_b128 v[170:173], v223 offset:8832

; __device__ __forceinline__ f32x4 mfma16(bf16x8 a, bf16x8 b, f32x4 c) { return __builtin_amdgcn_mfma_f32_16x16x32_bf16(a, b, c, 0, 0, 0); }
; __device__ void ph_score(const P& p, int* lds) {
;     ...
;       for (int ks = 0; ks < 4; ++ks) {
;         bf16x8 qf = *(const bf16x8*)(Qb + tok * 2048 + h * 256 + half * 128 + ks * 32 + fq * 8);
; #pragma unroll
;         for (int mt = 0; mt < 8; ++mt) {
;           bf16x8 kf = *(const bf16x8*)(Kb + (mt * 16 + fr) * 128 + ks * 32 + fq * 8);
;           sc[mt] = mfma16(kf, qf, sc[mt]);
;         }
;       }
	v_mfma_f32_16x16x32_bf16 v[174:177], v[182:185], v[158:161], v[174:177]


; __device__ __forceinline__ f32x4 mfma16(bf16x8 a, bf16x8 b, f32x4 c) { return __builtin_amdgcn_mfma_f32_16x16x32_bf16(a, b, c, 0, 0, 0); }
; __device__ void ph_score(const P& p, int* lds) {
;     ...
;       for (int ks = 0; ks < 4; ++ks) {
;         bf16x8 qf = *(const bf16x8*)(Qb + tok * 2048 + h * 256 + half * 128 + ks * 32 + fq * 8);
; #pragma unroll
;         for (int mt = 0; mt < 8; ++mt) {
;           bf16x8 kf = *(const bf16x8*)(Kb + (mt * 16 + fr) * 128 + ks * 32 + fq * 8);
;           sc[mt] = mfma16(kf, qf, sc[mt]);
;         }
;       }
	ds_read_b128 v[182:185], v223 offset:13184
	s_nop 0
	global_load_dwordx4 v[198:201], v[0:1], off offset:192
	v_mfma_f32_16x16x32_bf16 v[6:9], v[186:189], v[158:161], v[6:9]


; __device__ __forceinline__ f32x4 mfma16(bf16x8 a, bf16x8 b, f32x4 c) { return __builtin_amdgcn_mfma_f32_16x16x32_bf16(a, b, c, 0, 0, 0); }
; __device__ void ph_score(const P& p, int* lds) {
;     ...
;       for (int ks = 0; ks < 4; ++ks) {
;         bf16x8 qf = *(const bf16x8*)(Qb + tok * 2048 + h * 256 + half * 128 + ks * 32 + fq * 8);
; #pragma unroll
;         for (int mt = 0; mt < 8; ++mt) {
;           bf16x8 kf = *(const bf16x8*)(Kb + (mt * 16 + fr) * 128 + ks * 32 + fq * 8);
;           sc[mt] = mfma16(kf, qf, sc[mt]);
;         }
;       }
	ds_read_b128 v[186:189], v223 offset:192


; __device__ __forceinline__ f32x4 mfma16(bf16x8 a, bf16x8 b, f32x4 c) { return __builtin_amdgcn_mfma_f32_16x16x32_bf16(a, b, c, 0, 0, 0); }
; __device__ void ph_score(const P& p, int* lds) {
;     ...
;       for (int ks = 0; ks < 4; ++ks) {
;         bf16x8 qf = *(const bf16x8*)(Qb + tok * 2048 + h * 256 + half * 128 + ks * 32 + fq * 8);
; #pragma unroll
;         for (int mt = 0; mt < 8; ++mt) {
;           bf16x8 kf = *(const bf16x8*)(Kb + (mt * 16 + fr) * 128 + ks * 32 + fq * 8);
;           sc[mt] = mfma16(kf, qf, sc[mt]);
;         }
;       }
	ds_read_b128 v[158:161], v223 offset:17536
	s_waitcnt vmcnt(0) lgkmcnt(0)
	v_mfma_f32_16x16x32_bf16 v[2:5], v[194:197], v[190:193], v[2:5]
	v_mfma_f32_16x16x32_bf16 v[10:13], v[178:181], v[190:193], v[10:13]


; __device__ __forceinline__ f32x4 mfma16(bf16x8 a, bf16x8 b, f32x4 c) { return __builtin_amdgcn_mfma_f32_16x16x32_bf16(a, b, c, 0, 0, 0); }
; __device__ void ph_score(const P& p, int* lds) {
;     ...
;       for (int ks = 0; ks < 4; ++ks) {
;         bf16x8 qf = *(const bf16x8*)(Qb + tok * 2048 + h * 256 + half * 128 + ks * 32 + fq * 8);
; #pragma unroll
;         for (int mt = 0; mt < 8; ++mt) {
;           bf16x8 kf = *(const bf16x8*)(Kb + (mt * 16 + fr) * 128 + ks * 32 + fq * 8);
;           sc[mt] = mfma16(kf, qf, sc[mt]);
;         }
;       }
	ds_read_b128 v[178:181], v223 offset:26240


; __device__ __forceinline__ f32x4 mfma16(bf16x8 a, bf16x8 b, f32x4 c) { return __builtin_amdgcn_mfma_f32_16x16x32_bf16(a, b, c, 0, 0, 0); }
; __device__ void ph_score(const P& p, int* lds) {
;     ...
;       for (int ks = 0; ks < 4; ++ks) {
;         bf16x8 qf = *(const bf16x8*)(Qb + tok * 2048 + h * 256 + half * 128 + ks * 32 + fq * 8);
; #pragma unroll
;         for (int mt = 0; mt < 8; ++mt) {
;           bf16x8 kf = *(const bf16x8*)(Kb + (mt * 16 + fr) * 128 + ks * 32 + fq * 8);
;           sc[mt] = mfma16(kf, qf, sc[mt]);
;         }
;       }
	ds_read_b128 v[194:197], v223 offset:21888

; __device__ __forceinline__ f32x4 mfma16(bf16x8 a, bf16x8 b, f32x4 c) { return __builtin_amdgcn_mfma_f32_16x16x32_bf16(a, b, c, 0, 0, 0); }
; __device__ void ph_score(const P& p, int* lds) {
;     ...
;       for (int ks = 0; ks < 4; ++ks) {
;         bf16x8 qf = *(const bf16x8*)(Qb + tok * 2048 + h * 256 + half * 128 + ks * 32 + fq * 8);
; #pragma unroll
;         for (int mt = 0; mt < 8; ++mt) {
;           bf16x8 kf = *(const bf16x8*)(Kb + (mt * 16 + fr) * 128 + ks * 32 + fq * 8);
;           sc[mt] = mfma16(kf, qf, sc[mt]);
;         }
;       }
	v_mfma_f32_16x16x32_bf16 v[50:53], v[170:173], v[190:193], v[50:53]


; __device__ __forceinline__ f32x4 mfma16(bf16x8 a, bf16x8 b, f32x4 c) { return __builtin_amdgcn_mfma_f32_16x16x32_bf16(a, b, c, 0, 0, 0); }
; __device__ void ph_score(const P& p, int* lds) {
;     ...
;       for (int ks = 0; ks < 4; ++ks) {
;         bf16x8 qf = *(const bf16x8*)(Qb + tok * 2048 + h * 256 + half * 128 + ks * 32 + fq * 8);
; #pragma unroll
;         for (int mt = 0; mt < 8; ++mt) {
;           bf16x8 kf = *(const bf16x8*)(Kb + (mt * 16 + fr) * 128 + ks * 32 + fq * 8);
;           sc[mt] = mfma16(kf, qf, sc[mt]);
;         }
;       }
	ds_read_b128 v[170:173], v223 offset:30592

; __device__ __forceinline__ f32x4 mfma16(bf16x8 a, bf16x8 b, f32x4 c) { return __builtin_amdgcn_mfma_f32_16x16x32_bf16(a, b, c, 0, 0, 0); }
; __device__ void ph_score(const P& p, int* lds) {
;     ...
;       for (int ks = 0; ks < 4; ++ks) {
;         bf16x8 qf = *(const bf16x8*)(Qb + tok * 2048 + h * 256 + half * 128 + ks * 32 + fq * 8);
; #pragma unroll
;         for (int mt = 0; mt < 8; ++mt) {
;           bf16x8 kf = *(const bf16x8*)(Kb + (mt * 16 + fr) * 128 + ks * 32 + fq * 8);
;           sc[mt] = mfma16(kf, qf, sc[mt]);
;         }
;       }
	v_mfma_f32_16x16x32_bf16 v[154:157], v[182:185], v[190:193], v[154:157]


; __device__ __forceinline__ f32x4 mfma16(bf16x8 a, bf16x8 b, f32x4 c) { return __builtin_amdgcn_mfma_f32_16x16x32_bf16(a, b, c, 0, 0, 0); }
; __device__ void ph_score(const P& p, int* lds) {
;     ...
;       for (int ks = 0; ks < 4; ++ks) {
;         bf16x8 qf = *(const bf16x8*)(Qb + tok * 2048 + h * 256 + half * 128 + ks * 32 + fq * 8);
; #pragma unroll
;         for (int mt = 0; mt < 8; ++mt) {
;           bf16x8 kf = *(const bf16x8*)(Kb + (mt * 16 + fr) * 128 + ks * 32 + fq * 8);
;           sc[mt] = mfma16(kf, qf, sc[mt]);
;         }
;       }
	ds_read_b128 v[182:185], v223 offset:4544

; __device__ __forceinline__ f32x4 mfma16(bf16x8 a, bf16x8 b, f32x4 c) { return __builtin_amdgcn_mfma_f32_16x16x32_bf16(a, b, c, 0, 0, 0); }
; __device__ void ph_score(const P& p, int* lds) {
;     ...
;       for (int ks = 0; ks < 4; ++ks) {
;         bf16x8 qf = *(const bf16x8*)(Qb + tok * 2048 + h * 256 + half * 128 + ks * 32 + fq * 8);
; #pragma unroll
;         for (int mt = 0; mt < 8; ++mt) {
;           bf16x8 kf = *(const bf16x8*)(Kb + (mt * 16 + fr) * 128 + ks * 32 + fq * 8);
;           sc[mt] = mfma16(kf, qf, sc[mt]);
;         }
;       }
	v_mfma_f32_16x16x32_bf16 v[158:161], v[158:161], v[190:193], v[166:169]
	s_nop 2


; __device__ __forceinline__ f32x4 mfma16(bf16x8 a, bf16x8 b, f32x4 c) { return __builtin_amdgcn_mfma_f32_16x16x32_bf16(a, b, c, 0, 0, 0); }
; __device__ void ph_score(const P& p, int* lds) {
;     ...
;       for (int ks = 0; ks < 4; ++ks) {
;         bf16x8 qf = *(const bf16x8*)(Qb + tok * 2048 + h * 256 + half * 128 + ks * 32 + fq * 8);
; #pragma unroll
;         for (int mt = 0; mt < 8; ++mt) {
;           bf16x8 kf = *(const bf16x8*)(Kb + (mt * 16 + fr) * 128 + ks * 32 + fq * 8);
;           sc[mt] = mfma16(kf, qf, sc[mt]);
;         }
;       }
	ds_read_b128 v[166:169], v223 offset:8896

; __device__ __forceinline__ f32x4 mfma16(bf16x8 a, bf16x8 b, f32x4 c) { return __builtin_amdgcn_mfma_f32_16x16x32_bf16(a, b, c, 0, 0, 0); }
; __device__ void ph_score(const P& p, int* lds) {
;     ...
;       for (int ks = 0; ks < 4; ++ks) {
;         bf16x8 qf = *(const bf16x8*)(Qb + tok * 2048 + h * 256 + half * 128 + ks * 32 + fq * 8);
; #pragma unroll
;         for (int mt = 0; mt < 8; ++mt) {
;           bf16x8 kf = *(const bf16x8*)(Kb + (mt * 16 + fr) * 128 + ks * 32 + fq * 8);
;           sc[mt] = mfma16(kf, qf, sc[mt]);
;         }
;       }
	v_mfma_f32_16x16x32_bf16 v[2:5], v[186:189], v[198:201], v[2:5]
	s_waitcnt vmcnt(0) lgkmcnt(0)
	v_mfma_f32_16x16x32_bf16 v[174:177], v[178:181], v[190:193], v[174:177]
	v_mfma_f32_16x16x32_bf16 v[162:165], v[194:197], v[190:193], v[162:165]


; __device__ __forceinline__ f32x4 mfma16(bf16x8 a, bf16x8 b, f32x4 c) { return __builtin_amdgcn_mfma_f32_16x16x32_bf16(a, b, c, 0, 0, 0); }
; __device__ void ph_score(const P& p, int* lds) {
;     ...
;       for (int ks = 0; ks < 4; ++ks) {
;         bf16x8 qf = *(const bf16x8*)(Qb + tok * 2048 + h * 256 + half * 128 + ks * 32 + fq * 8);
; #pragma unroll
;         for (int mt = 0; mt < 8; ++mt) {
;           bf16x8 kf = *(const bf16x8*)(Kb + (mt * 16 + fr) * 128 + ks * 32 + fq * 8);
;           sc[mt] = mfma16(kf, qf, sc[mt]);
;         }
;       }
	ds_read_b128 v[194:197], v223 offset:17600


; __device__ __forceinline__ f32x4 mfma16(bf16x8 a, bf16x8 b, f32x4 c) { return __builtin_amdgcn_mfma_f32_16x16x32_bf16(a, b, c, 0, 0, 0); }
; __device__ void ph_score(const P& p, int* lds) {
;     ...
;       for (int ks = 0; ks < 4; ++ks) {
;         bf16x8 qf = *(const bf16x8*)(Qb + tok * 2048 + h * 256 + half * 128 + ks * 32 + fq * 8);
; #pragma unroll
;         for (int mt = 0; mt < 8; ++mt) {
;           bf16x8 kf = *(const bf16x8*)(Kb + (mt * 16 + fr) * 128 + ks * 32 + fq * 8);
;           sc[mt] = mfma16(kf, qf, sc[mt]);
;         }
;       }
	ds_read_b128 v[178:181], v223 offset:13248

; __device__ __forceinline__ f32x4 mfma16(bf16x8 a, bf16x8 b, f32x4 c) { return __builtin_amdgcn_mfma_f32_16x16x32_bf16(a, b, c, 0, 0, 0); }
; __device__ void ph_score(const P& p, int* lds) {
;     ...
;       for (int ks = 0; ks < 4; ++ks) {
;         bf16x8 qf = *(const bf16x8*)(Qb + tok * 2048 + h * 256 + half * 128 + ks * 32 + fq * 8);
; #pragma unroll
;         for (int mt = 0; mt < 8; ++mt) {
;           bf16x8 kf = *(const bf16x8*)(Kb + (mt * 16 + fr) * 128 + ks * 32 + fq * 8);
;           sc[mt] = mfma16(kf, qf, sc[mt]);
;         }
;       }
	v_mfma_f32_16x16x32_bf16 v[6:9], v[170:173], v[190:193], v[6:9]


; __device__ __forceinline__ f32x4 mfma16(bf16x8 a, bf16x8 b, f32x4 c) { return __builtin_amdgcn_mfma_f32_16x16x32_bf16(a, b, c, 0, 0, 0); }
; __device__ void ph_score(const P& p, int* lds) {
;     ...
;       for (int ks = 0; ks < 4; ++ks) {
;         bf16x8 qf = *(const bf16x8*)(Qb + tok * 2048 + h * 256 + half * 128 + ks * 32 + fq * 8);
; #pragma unroll
;         for (int mt = 0; mt < 8; ++mt) {
;           bf16x8 kf = *(const bf16x8*)(Kb + (mt * 16 + fr) * 128 + ks * 32 + fq * 8);
;           sc[mt] = mfma16(kf, qf, sc[mt]);
;         }
;       }
	ds_read_b128 v[170:173], v223 offset:21952


; __device__ __forceinline__ f32x4 mfma16(bf16x8 a, bf16x8 b, f32x4 c) { return __builtin_amdgcn_mfma_f32_16x16x32_bf16(a, b, c, 0, 0, 0); }
; __device__ void ph_score(const P& p, int* lds) {
;     ...
;       for (int ks = 0; ks < 4; ++ks) {
;         bf16x8 qf = *(const bf16x8*)(Qb + tok * 2048 + h * 256 + half * 128 + ks * 32 + fq * 8);
; #pragma unroll
;         for (int mt = 0; mt < 8; ++mt) {
;           bf16x8 kf = *(const bf16x8*)(Kb + (mt * 16 + fr) * 128 + ks * 32 + fq * 8);
;           sc[mt] = mfma16(kf, qf, sc[mt]);
;         }
;       }
	ds_read_b128 v[186:189], v223 offset:26304

; __device__ __forceinline__ f32x4 mfma16(bf16x8 a, bf16x8 b, f32x4 c) { return __builtin_amdgcn_mfma_f32_16x16x32_bf16(a, b, c, 0, 0, 0); }
; __device__ void ph_score(const P& p, int* lds) {
;     ...
;       for (int ks = 0; ks < 4; ++ks) {
;         bf16x8 qf = *(const bf16x8*)(Qb + tok * 2048 + h * 256 + half * 128 + ks * 32 + fq * 8);
; #pragma unroll
;         for (int mt = 0; mt < 8; ++mt) {
;           bf16x8 kf = *(const bf16x8*)(Kb + (mt * 16 + fr) * 128 + ks * 32 + fq * 8);
;           sc[mt] = mfma16(kf, qf, sc[mt]);
;         }
;       }
	v_mfma_f32_16x16x32_bf16 v[10:13], v[182:185], v[198:201], v[10:13]


; __device__ __forceinline__ int key_pack(float v, int payload, int mask) {
;   int b = (__float_as_int(v) & ~mask) | payload;
;   return b ^ ((b >> 31) & 0x7fffffff);
; }
; __device__ void ph_score(const P& p, int* lds) {
;     ...
; #pragma unroll
;       for (int mt = 0; mt < 4; ++mt)
; #pragma unroll
;         for (int r = 0; r < 4; ++r) {
;           a[mt * 4 + r] = key_pack(sc[mt][r], mt * 16 + fq * 4 + r, 0x7f);
;           b[mt * 4 + r] = key_pack(sc[mt + 4][r], (mt + 4) * 16 + fq * 4 + r, 0x7f);
;         }
;       sort16p(a);
	ds_read_b128 v[182:185], v223 offset:30656
	v_and_b32_e32 v14, 0xffffff80, v2
	v_ashrrev_i32_e32 v2, 31, v2
	v_and_b32_e32 v2, 0x7fffffff, v2
	v_bitop3_b32 v2, v14, v2, v20 bitop3:0x36
	v_mfma_f32_16x16x32_bf16 v[50:53], v[166:169], v[198:201], v[50:53]
	s_waitcnt vmcnt(0) lgkmcnt(0)
	v_mfma_f32_16x16x32_bf16 v[158:161], v[194:197], v[198:201], v[158:161]
	s_nop 7
	v_ashrrev_i32_e32 v15, 31, v158
	v_and_b32_e32 v14, 0xffffff80, v158
	v_and_b32_e32 v15, 0x7fffffff, v15
	v_bitop3_b32 v14, v14, v15, v56 bitop3:0x36
	v_and_b32_e32 v15, 0xffffff80, v3
	v_ashrrev_i32_e32 v3, 31, v3
	v_and_b32_e32 v3, 0x7fffffff, v3
	v_ashrrev_i32_e32 v18, 31, v159
	v_bitop3_b32 v3, v15, v3, v57 bitop3:0x36
	v_and_b32_e32 v15, 0xffffff80, v159
	v_and_b32_e32 v18, 0x7fffffff, v18
	v_bitop3_b32 v15, v15, v18, v58 bitop3:0x36
	v_and_b32_e32 v18, 0xffffff80, v4
	v_ashrrev_i32_e32 v4, 31, v4
	v_and_b32_e32 v4, 0x7fffffff, v4
	v_ashrrev_i32_e32 v46, 31, v160
	v_bitop3_b32 v4, v18, v4, v59 bitop3:0x36
	v_and_b32_e32 v18, 0xffffff80, v160
	v_and_b32_e32 v46, 0x7fffffff, v46
	v_mfma_f32_16x16x32_bf16 v[162:165], v[170:173], v[198:201], v[162:165]
	v_bitop3_b32 v18, v18, v46, v60 bitop3:0x36
	v_and_b32_e32 v46, 0xffffff80, v5
	v_ashrrev_i32_e32 v5, 31, v5
	v_and_b32_e32 v5, 0x7fffffff, v5
	v_ashrrev_i32_e32 v47, 31, v161
	v_bitop3_b32 v5, v46, v5, v61 bitop3:0x36
	v_and_b32_e32 v46, 0xffffff80, v161
	v_and_b32_e32 v47, 0x7fffffff, v47
	v_bitop3_b32 v46, v46, v47, v62 bitop3:0x36
	v_and_b32_e32 v47, 0xffffff80, v10
	v_ashrrev_i32_e32 v10, 31, v10
	v_and_b32_e32 v10, 0x7fffffff, v10
	v_ashrrev_i32_e32 v48, 31, v162
	v_bitop3_b32 v10, v47, v10, v63 bitop3:0x36
	v_and_b32_e32 v47, 0xffffff80, v162
	v_and_b32_e32 v48, 0x7fffffff, v48
	v_bitop3_b32 v47, v47, v48, v64 bitop3:0x36
	v_and_b32_e32 v48, 0xffffff80, v11
	v_ashrrev_i32_e32 v11, 31, v11
	v_and_b32_e32 v11, 0x7fffffff, v11
	v_ashrrev_i32_e32 v153, 31, v163
	v_bitop3_b32 v11, v48, v11, v65 bitop3:0x36
	v_and_b32_e32 v48, 0xffffff80, v163
	v_and_b32_e32 v153, 0x7fffffff, v153
	v_bitop3_b32 v48, v48, v153, v66 bitop3:0x36
	v_and_b32_e32 v153, 0xffffff80, v12
	v_ashrrev_i32_e32 v12, 31, v12
	v_and_b32_e32 v12, 0x7fffffff, v12
	v_ashrrev_i32_e32 v158, 31, v164
	v_bitop3_b32 v12, v153, v12, v67 bitop3:0x36
	v_and_b32_e32 v153, 0xffffff80, v164
	v_and_b32_e32 v158, 0x7fffffff, v158
	v_mfma_f32_16x16x32_bf16 v[166:169], v[186:189], v[198:201], v[174:177]
	v_bitop3_b32 v153, v153, v158, v68 bitop3:0x36
	v_and_b32_e32 v158, 0xffffff80, v13
	v_ashrrev_i32_e32 v13, 31, v13
	v_and_b32_e32 v13, 0x7fffffff, v13
	v_ashrrev_i32_e32 v159, 31, v165
	v_bitop3_b32 v13, v158, v13, v69 bitop3:0x36
	v_and_b32_e32 v158, 0xffffff80, v165
	v_and_b32_e32 v159, 0x7fffffff, v159
	v_bitop3_b32 v158, v158, v159, v70 bitop3:0x36
	v_and_b32_e32 v159, 0xffffff80, v50
	v_ashrrev_i32_e32 v50, 31, v50
	v_and_b32_e32 v50, 0x7fffffff, v50
	v_ashrrev_i32_e32 v160, 31, v166
	v_bitop3_b32 v50, v159, v50, v71 bitop3:0x36
	v_and_b32_e32 v159, 0xffffff80, v166
	v_and_b32_e32 v160, 0x7fffffff, v160
	v_bitop3_b32 v159, v159, v160, v72 bitop3:0x36
	v_and_b32_e32 v160, 0xffffff80, v51
	v_ashrrev_i32_e32 v51, 31, v51
	v_and_b32_e32 v51, 0x7fffffff, v51
	v_ashrrev_i32_e32 v161, 31, v167
	v_bitop3_b32 v51, v160, v51, v73 bitop3:0x36
	v_and_b32_e32 v160, 0xffffff80, v167
	v_and_b32_e32 v161, 0x7fffffff, v161
	v_bitop3_b32 v160, v160, v161, v74 bitop3:0x36
	v_and_b32_e32 v161, 0xffffff80, v52
	v_ashrrev_i32_e32 v52, 31, v52
	v_and_b32_e32 v52, 0x7fffffff, v52
	v_ashrrev_i32_e32 v162, 31, v168
	v_mfma_f32_16x16x32_bf16 v[154:157], v[178:181], v[198:201], v[154:157]
	v_bitop3_b32 v52, v161, v52, v75 bitop3:0x36
	v_and_b32_e32 v161, 0xffffff80, v168
	v_and_b32_e32 v162, 0x7fffffff, v162
	v_bitop3_b32 v161, v161, v162, v76 bitop3:0x36
	v_and_b32_e32 v162, 0xffffff80, v53
	v_ashrrev_i32_e32 v53, 31, v53
	v_mfma_f32_16x16x32_bf16 v[6:9], v[182:185], v[198:201], v[6:9]
	v_and_b32_e32 v53, 0x7fffffff, v53
	v_ashrrev_i32_e32 v163, 31, v169
	v_bitop3_b32 v53, v162, v53, v77 bitop3:0x36
	v_and_b32_e32 v162, 0xffffff80, v169
	v_and_b32_e32 v163, 0x7fffffff, v163
	v_bitop3_b32 v162, v162, v163, v78 bitop3:0x36
	v_and_b32_e32 v163, 0xffffff80, v154
	v_ashrrev_i32_e32 v154, 31, v154
	v_and_b32_e32 v154, 0x7fffffff, v154
	v_bitop3_b32 v154, v163, v154, v79 bitop3:0x36
	v_and_b32_e32 v163, 0xffffff80, v6
	v_ashrrev_i32_e32 v6, 31, v6
	v_and_b32_e32 v6, 0x7fffffff, v6
	v_bitop3_b32 v6, v163, v6, v80 bitop3:0x36
	v_and_b32_e32 v163, 0xffffff80, v155
	v_ashrrev_i32_e32 v155, 31, v155
	v_and_b32_e32 v155, 0x7fffffff, v155
	v_bitop3_b32 v155, v163, v155, v81 bitop3:0x36
	v_and_b32_e32 v163, 0xffffff80, v7
	v_ashrrev_i32_e32 v7, 31, v7
	v_and_b32_e32 v7, 0x7fffffff, v7
	v_bitop3_b32 v7, v163, v7, v82 bitop3:0x36
	v_and_b32_e32 v163, 0xffffff80, v156
	v_ashrrev_i32_e32 v156, 31, v156
	v_and_b32_e32 v156, 0x7fffffff, v156
	v_bitop3_b32 v156, v163, v156, v83 bitop3:0x36
	v_and_b32_e32 v163, 0xffffff80, v8
	v_ashrrev_i32_e32 v8, 31, v8
	v_and_b32_e32 v8, 0x7fffffff, v8
	v_bitop3_b32 v8, v163, v8, v84 bitop3:0x36
	v_and_b32_e32 v163, 0xffffff80, v157
	v_ashrrev_i32_e32 v157, 31, v157
	v_and_b32_e32 v157, 0x7fffffff, v157
	v_bitop3_b32 v157, v163, v157, v85 bitop3:0x36
	v_and_b32_e32 v163, 0xffffff80, v9
	v_ashrrev_i32_e32 v9, 31, v9
	v_and_b32_e32 v9, 0x7fffffff, v9
	v_bitop3_b32 v9, v163, v9, v86 bitop3:0x36
	v_max_i32_e32 v163, v2, v3
	v_min_i32_e32 v2, v2, v3
	v_max_i32_e32 v3, v5, v4
	v_min_i32_e32 v4, v5, v4
	v_max_i32_e32 v5, v10, v11
	v_min_i32_e32 v10, v10, v11
	v_max_i32_e32 v11, v13, v12
	v_min_i32_e32 v12, v13, v12
	v_max_i32_e32 v13, v50, v51
	v_min_i32_e32 v50, v50, v51
; __device__ __forceinline__ void sort16p(int (&v)[16]) {
; #pragma unroll
;   for (int k = 2; k <= 16; k <<= 1)
; #pragma unroll
;     for (int j = k >> 1; j > 0; j >>= 1)
; #pragma unroll
;       for (int i = 0; i < 16; ++i) {
;         int l = i ^ j;
;         if (l > i) {
;           if ((i & k) == 0) { CE1(v[i], v[l]); }
;           else { CE1(v[l], v[i]); }
;         }
;       }
; }
	v_max_i32_e32 v51, v53, v52
	v_min_i32_e32 v52, v53, v52
	v_max_i32_e32 v53, v154, v155
	v_min_i32_e32 v154, v154, v155
	v_max_i32_e32 v155, v157, v156
	v_min_i32_e32 v156, v157, v156
	v_max_i32_e32 v157, v163, v4
	v_min_i32_e32 v4, v163, v4
	v_max_i32_e32 v163, v2, v3
	v_min_i32_e32 v2, v2, v3
	v_max_i32_e32 v3, v12, v5
	v_min_i32_e32 v5, v12, v5
	v_max_i32_e32 v12, v11, v10
	v_min_i32_e32 v10, v11, v10
	v_max_i32_e32 v11, v13, v52
	v_min_i32_e32 v13, v13, v52
	v_max_i32_e32 v52, v50, v51
	v_min_i32_e32 v50, v50, v51
	v_max_i32_e32 v51, v156, v53
	v_min_i32_e32 v53, v156, v53
	v_max_i32_e32 v156, v155, v154
	v_min_i32_e32 v154, v155, v154
	v_max_i32_e32 v155, v157, v163
	v_min_i32_e32 v157, v157, v163
	v_max_i32_e32 v163, v4, v2
	v_min_i32_e32 v2, v4, v2
	v_max_i32_e32 v4, v10, v5
	v_min_i32_e32 v5, v10, v5
	v_max_i32_e32 v10, v12, v3
	v_min_i32_e32 v3, v12, v3
	v_max_i32_e32 v12, v11, v52
	v_min_i32_e32 v11, v11, v52
	v_max_i32_e32 v52, v13, v50
	v_min_i32_e32 v13, v13, v50
	v_max_i32_e32 v50, v154, v53
	v_min_i32_e32 v53, v154, v53
	v_max_i32_e32 v154, v156, v51
	v_min_i32_e32 v51, v156, v51
	v_max_i32_e32 v156, v155, v5
	v_min_i32_e32 v5, v155, v5
	v_max_i32_e32 v155, v157, v4
	v_min_i32_e32 v4, v157, v4
	v_max_i32_e32 v157, v163, v3
	v_min_i32_e32 v3, v163, v3
	v_max_i32_e32 v163, v2, v10
	v_min_i32_e32 v2, v2, v10
	v_max_i32_e32 v10, v53, v12
	v_min_i32_e32 v12, v53, v12
	v_max_i32_e32 v53, v50, v11
	v_min_i32_e32 v11, v50, v11
	v_max_i32_e32 v50, v51, v52
	v_min_i32_e32 v51, v51, v52
	v_max_i32_e32 v52, v154, v13
	v_min_i32_e32 v13, v154, v13
	v_max_i32_e32 v154, v156, v157
	v_min_i32_e32 v156, v156, v157
	v_max_i32_e32 v157, v155, v163
	v_min_i32_e32 v155, v155, v163
	v_max_i32_e32 v163, v5, v3
	v_min_i32_e32 v3, v5, v3
	v_max_i32_e32 v5, v4, v2
	v_min_i32_e32 v2, v4, v2
	v_max_i32_e32 v4, v51, v12
	v_min_i32_e32 v12, v51, v12
	v_max_i32_e32 v51, v13, v11
	v_min_i32_e32 v11, v13, v11
	v_max_i32_e32 v13, v50, v10
	v_min_i32_e32 v10, v50, v10
	v_max_i32_e32 v50, v52, v53
	v_min_i32_e32 v52, v52, v53
	v_max_i32_e32 v53, v154, v157
	v_min_i32_e32 v154, v154, v157
	v_max_i32_e32 v157, v156, v155
	v_min_i32_e32 v155, v156, v155
	v_max_i32_e32 v156, v163, v5
	v_min_i32_e32 v5, v163, v5
	v_max_i32_e32 v163, v3, v2
	v_min_i32_e32 v2, v3, v2
	v_max_i32_e32 v3, v11, v12
	v_min_i32_e32 v11, v11, v12
	v_max_i32_e32 v12, v51, v4
	v_min_i32_e32 v4, v51, v4
	v_max_i32_e32 v51, v52, v10
	v_min_i32_e32 v10, v52, v10
	v_max_i32_e32 v52, v50, v13
	v_min_i32_e32 v13, v50, v13
	v_max_i32_e32 v50, v53, v11
	v_min_i32_e32 v11, v53, v11
	v_max_i32_e32 v53, v154, v3
	v_min_i32_e32 v3, v154, v3
	v_max_i32_e32 v154, v157, v4
	v_min_i32_e32 v4, v157, v4
	v_max_i32_e32 v157, v155, v12
	v_min_i32_e32 v12, v155, v12
	v_max_i32_e32 v155, v156, v10
	v_min_i32_e32 v10, v156, v10
	v_max_i32_e32 v156, v5, v51
	v_min_i32_e32 v5, v5, v51
	v_max_i32_e32 v51, v163, v13
	v_min_i32_e32 v13, v163, v13
	v_max_i32_e32 v163, v2, v52
	v_min_i32_e32 v2, v2, v52
	v_max_i32_e32 v52, v50, v155
	v_min_i32_e32 v50, v50, v155
	v_max_i32_e32 v155, v53, v156
	v_min_i32_e32 v53, v53, v156
	v_max_i32_e32 v156, v154, v51
	v_min_i32_e32 v51, v154, v51
	v_max_i32_e32 v154, v157, v163
	v_min_i32_e32 v157, v157, v163
	v_max_i32_e32 v163, v11, v10
	v_min_i32_e32 v10, v11, v10
	v_max_i32_e32 v11, v3, v5
	v_min_i32_e32 v3, v3, v5
	v_max_i32_e32 v5, v4, v13
	v_min_i32_e32 v4, v4, v13
	v_max_i32_e32 v13, v12, v2
	v_min_i32_e32 v2, v12, v2
	v_max_i32_e32 v12, v52, v156
	v_min_i32_e32 v52, v52, v156
	v_max_i32_e32 v156, v155, v154
	v_min_i32_e32 v154, v155, v154
	v_max_i32_e32 v155, v50, v51
	v_min_i32_e32 v50, v50, v51
	v_max_i32_e32 v51, v53, v157
	v_min_i32_e32 v53, v53, v157
	v_max_i32_e32 v157, v163, v5
	v_min_i32_e32 v5, v163, v5
	v_max_i32_e32 v163, v11, v13
	v_min_i32_e32 v11, v11, v13
	v_max_i32_e32 v13, v10, v4
	v_min_i32_e32 v4, v10, v4
	v_max_i32_e32 v10, v3, v2
	v_min_i32_e32 v2, v3, v2
	v_min_i32_e32 v3, v12, v156
	v_min_i32_e32 v164, v52, v154
	v_min_i32_e32 v165, v155, v51
	v_min_i32_e32 v166, v50, v53
	v_min_i32_e32 v167, v157, v163
	v_min_i32_e32 v168, v5, v11
	v_min_i32_e32 v169, v13, v10
	v_min_i32_e32 v170, v4, v2
	v_max_i32_e32 v171, v14, v15
	v_min_i32_e32 v14, v14, v15
	v_max_i32_e32 v15, v46, v18
	v_min_i32_e32 v18, v46, v18
	v_max_i32_e32 v46, v47, v48
	v_min_i32_e32 v47, v47, v48
	v_max_i32_e32 v48, v158, v153
	v_min_i32_e32 v153, v158, v153
	v_max_i32_e32 v158, v159, v160
	v_min_i32_e32 v159, v159, v160
	v_max_i32_e32 v160, v162, v161
	v_min_i32_e32 v161, v162, v161
	v_max_i32_e32 v162, v6, v7
	v_min_i32_e32 v6, v6, v7
	v_max_i32_e32 v7, v9, v8
	v_min_i32_e32 v8, v9, v8
	v_max_i32_e32 v9, v171, v18
	v_min_i32_e32 v18, v171, v18
	v_max_i32_e32 v171, v14, v15
	v_min_i32_e32 v14, v14, v15
	v_max_i32_e32 v15, v153, v46
	v_min_i32_e32 v46, v153, v46
	v_max_i32_e32 v153, v48, v47
	v_min_i32_e32 v47, v48, v47
	v_max_i32_e32 v48, v158, v161
	v_min_i32_e32 v158, v158, v161
	v_max_i32_e32 v161, v159, v160
	v_min_i32_e32 v159, v159, v160
	v_max_i32_e32 v160, v8, v162
	v_min_i32_e32 v8, v8, v162
	v_max_i32_e32 v162, v7, v6
	v_min_i32_e32 v6, v7, v6
	v_max_i32_e32 v7, v9, v171
	v_min_i32_e32 v9, v9, v171
	v_max_i32_e32 v171, v18, v14
	v_min_i32_e32 v14, v18, v14
	v_max_i32_e32 v18, v47, v46
	v_min_i32_e32 v46, v47, v46
	v_max_i32_e32 v47, v153, v15
	v_min_i32_e32 v15, v153, v15
	v_max_i32_e32 v153, v48, v161
	v_min_i32_e32 v48, v48, v161
	v_max_i32_e32 v161, v158, v159
	v_min_i32_e32 v158, v158, v159
	v_max_i32_e32 v159, v6, v8
	v_min_i32_e32 v6, v6, v8
	v_max_i32_e32 v8, v162, v160
	v_min_i32_e32 v160, v162, v160
	v_max_i32_e32 v162, v7, v46
	v_min_i32_e32 v7, v7, v46
; __device__ __forceinline__ void sort16p(int (&v)[16]) {
; #pragma unroll
;   for (int k = 2; k <= 16; k <<= 1)
; #pragma unroll
;     for (int j = k >> 1; j > 0; j >>= 1)
; #pragma unroll
;       for (int i = 0; i < 16; ++i) {
;         int l = i ^ j;
;         if (l > i) {
;           if ((i & k) == 0) { CE1(v[i], v[l]); }
;           else { CE1(v[l], v[i]); }
;         }
;       }
; }
; __device__ __forceinline__ void merge16p(int (&a)[16], const int (&b)[16]) {
; #pragma unroll
;   for (int i = 0; i < 16; ++i) a[i] = max(a[i], b[15 - i]);
; #pragma unroll
;   for (int j = 8; j > 0; j >>= 1)
; #pragma unroll
;     for (int i = 0; i < 16; ++i) {
;       int l = i ^ j;
;       if (l > i) { CE1(a[i], a[l]); }
;     }
; }
; __device__ __forceinline__ void xmerge16p(int (&a)[16], int mask) {
;   int b[16];
; #pragma unroll
;   for (int i = 0; i < 16; ++i) b[i] = (mask == 16) ? __builtin_amdgcn_ds_swizzle(a[i], 0x401F) : __shfl_xor(a[i], 32);
;   merge16p(a, b);
; }
	v_max_i32_e32 v46, v9, v18
	v_min_i32_e32 v9, v9, v18
	v_max_i32_e32 v18, v171, v15
	v_min_i32_e32 v15, v171, v15
	v_max_i32_e32 v171, v14, v47
	v_min_i32_e32 v14, v14, v47
	v_max_i32_e32 v47, v6, v153
	v_min_i32_e32 v6, v6, v153
	v_max_i32_e32 v153, v159, v48
	v_min_i32_e32 v48, v159, v48
	v_max_i32_e32 v159, v160, v161
	v_min_i32_e32 v160, v160, v161
	v_max_i32_e32 v161, v8, v158
	v_min_i32_e32 v8, v8, v158
	v_max_i32_e32 v158, v162, v18
	v_min_i32_e32 v18, v162, v18
	v_max_i32_e32 v162, v46, v171
	v_min_i32_e32 v46, v46, v171
	v_max_i32_e32 v171, v7, v15
	v_min_i32_e32 v7, v7, v15
	v_max_i32_e32 v15, v9, v14
	v_min_i32_e32 v9, v9, v14
	v_max_i32_e32 v14, v160, v6
	v_min_i32_e32 v6, v160, v6
	v_max_i32_e32 v160, v8, v48
	v_min_i32_e32 v8, v8, v48
	v_max_i32_e32 v48, v159, v47
	v_min_i32_e32 v47, v159, v47
	v_max_i32_e32 v159, v161, v153
	v_min_i32_e32 v153, v161, v153
	v_max_i32_e32 v161, v158, v162
	v_min_i32_e32 v158, v158, v162
	v_max_i32_e32 v162, v18, v46
	v_min_i32_e32 v18, v18, v46
	v_max_i32_e32 v46, v171, v15
	v_min_i32_e32 v15, v171, v15
	v_max_i32_e32 v171, v7, v9
	v_min_i32_e32 v7, v7, v9
	v_max_i32_e32 v9, v8, v6
	v_min_i32_e32 v6, v8, v6
	v_max_i32_e32 v8, v160, v14
	v_min_i32_e32 v14, v160, v14
	v_max_i32_e32 v160, v153, v47
	v_min_i32_e32 v47, v153, v47
	v_max_i32_e32 v153, v159, v48
	v_min_i32_e32 v48, v159, v48
	v_max_i32_e32 v159, v161, v6
	v_min_i32_e32 v6, v161, v6
	v_max_i32_e32 v161, v158, v9
	v_min_i32_e32 v9, v158, v9
	v_max_i32_e32 v158, v162, v14
	v_min_i32_e32 v14, v162, v14
	v_max_i32_e32 v162, v18, v8
	v_min_i32_e32 v8, v18, v8
	v_max_i32_e32 v18, v46, v47
	v_min_i32_e32 v46, v46, v47
	v_max_i32_e32 v47, v15, v160
	v_min_i32_e32 v15, v15, v160
	v_max_i32_e32 v160, v171, v48
	v_min_i32_e32 v48, v171, v48
	v_max_i32_e32 v171, v7, v153
	v_min_i32_e32 v7, v7, v153
	v_max_i32_e32 v153, v159, v18
	v_min_i32_e32 v18, v159, v18
	v_max_i32_e32 v159, v161, v47
	v_min_i32_e32 v47, v161, v47
	v_max_i32_e32 v161, v158, v160
	v_min_i32_e32 v158, v158, v160
	v_max_i32_e32 v160, v162, v171
	v_min_i32_e32 v162, v162, v171
	v_max_i32_e32 v171, v6, v46
	v_min_i32_e32 v6, v6, v46
	v_max_i32_e32 v46, v9, v15
	v_min_i32_e32 v9, v9, v15
	v_max_i32_e32 v15, v14, v48
	v_min_i32_e32 v14, v14, v48
	v_max_i32_e32 v48, v8, v7
	v_min_i32_e32 v7, v8, v7
	v_max_i32_e32 v8, v153, v161
	v_min_i32_e32 v153, v153, v161
	v_max_i32_e32 v161, v159, v160
	v_min_i32_e32 v159, v159, v160
	v_max_i32_e32 v160, v18, v158
	v_min_i32_e32 v18, v18, v158
	v_max_i32_e32 v158, v47, v162
	v_min_i32_e32 v47, v47, v162
	v_max_i32_e32 v162, v171, v15
	v_min_i32_e32 v15, v171, v15
	v_max_i32_e32 v171, v46, v48
	v_min_i32_e32 v46, v46, v48
	v_max_i32_e32 v48, v6, v14
	v_min_i32_e32 v6, v6, v14
	v_max_i32_e32 v14, v9, v7
	v_min_i32_e32 v7, v9, v7
	v_min_i32_e32 v9, v8, v161
	v_min_i32_e32 v172, v153, v159
	v_min_i32_e32 v173, v160, v158
	v_min_i32_e32 v174, v18, v47
	v_min_i32_e32 v175, v162, v171
	v_min_i32_e32 v176, v15, v46
	v_min_i32_e32 v177, v48, v14
	v_min_i32_e32 v178, v6, v7
	v_max3_i32 v12, v12, v156, v178
	v_max3_i32 v3, v3, v6, v7
	v_max3_i32 v6, v52, v154, v177
	v_max3_i32 v7, v164, v48, v14
	v_max3_i32 v14, v155, v51, v176
	v_max3_i32 v15, v165, v15, v46
	v_max3_i32 v46, v50, v53, v175
	v_max3_i32 v48, v166, v162, v171
	v_max3_i32 v50, v157, v163, v174
	v_max3_i32 v18, v167, v18, v47
	v_max3_i32 v5, v5, v11, v173
	v_max3_i32 v11, v168, v160, v158
	v_max3_i32 v10, v13, v10, v172
	v_max3_i32 v13, v169, v153, v159
	v_max3_i32 v2, v4, v2, v9
	v_max3_i32 v4, v170, v8, v161
	v_max_i32_e32 v8, v12, v50
	v_min_i32_e32 v9, v12, v50
	v_max_i32_e32 v12, v3, v18
	v_min_i32_e32 v3, v3, v18
	v_max_i32_e32 v18, v6, v5
	v_min_i32_e32 v5, v6, v5
	v_max_i32_e32 v6, v7, v11
	v_min_i32_e32 v7, v7, v11
	v_max_i32_e32 v11, v14, v10
	v_min_i32_e32 v10, v14, v10
	v_max_i32_e32 v14, v15, v13
	v_min_i32_e32 v13, v15, v13
	v_max_i32_e32 v15, v46, v2
	v_min_i32_e32 v2, v46, v2
	v_max_i32_e32 v46, v48, v4
	v_min_i32_e32 v4, v48, v4
	v_max_i32_e32 v47, v8, v11
	v_min_i32_e32 v8, v8, v11
	v_max_i32_e32 v11, v12, v14
	v_min_i32_e32 v12, v12, v14
	v_max_i32_e32 v14, v18, v15
	v_min_i32_e32 v15, v18, v15
	v_max_i32_e32 v18, v6, v46
	v_min_i32_e32 v6, v6, v46
	v_max_i32_e32 v46, v9, v10
	v_min_i32_e32 v9, v9, v10
	v_max_i32_e32 v10, v3, v13
	v_min_i32_e32 v3, v3, v13
	v_max_i32_e32 v13, v5, v2
	v_min_i32_e32 v2, v5, v2
	v_max_i32_e32 v5, v7, v4
	v_min_i32_e32 v4, v7, v4
	v_max_i32_e32 v7, v47, v14
	v_min_i32_e32 v14, v47, v14
	v_max_i32_e32 v47, v11, v18
	v_min_i32_e32 v11, v11, v18
	v_max_i32_e32 v18, v8, v15
	v_min_i32_e32 v8, v8, v15
	v_max_i32_e32 v15, v12, v6
	v_min_i32_e32 v6, v12, v6
	v_max_i32_e32 v12, v46, v13
	v_min_i32_e32 v13, v46, v13
	v_max_i32_e32 v46, v10, v5
	v_min_i32_e32 v5, v10, v5
	v_max_i32_e32 v10, v9, v2
	v_min_i32_e32 v2, v9, v2
	v_max_i32_e32 v9, v3, v4
	v_min_i32_e32 v3, v3, v4
	v_max_i32_e32 v4, v7, v47
	v_min_i32_e32 v7, v7, v47
	v_max_i32_e32 v47, v14, v11
	v_min_i32_e32 v11, v14, v11
	v_max_i32_e32 v14, v18, v15
	v_min_i32_e32 v15, v18, v15
	v_max_i32_e32 v18, v8, v6
	v_min_i32_e32 v6, v8, v6
	v_max_i32_e32 v8, v12, v46
	v_min_i32_e32 v12, v12, v46
	v_max_i32_e32 v46, v13, v5
	v_min_i32_e32 v5, v13, v5
	v_max_i32_e32 v13, v10, v9
	v_min_i32_e32 v9, v10, v9
	v_max_i32_e32 v10, v2, v3
	v_min_i32_e32 v2, v2, v3
	ds_swizzle_b32 v3, v4 offset:swizzle(SWAP,16)
	ds_swizzle_b32 v48, v7 offset:swizzle(SWAP,16)
	ds_swizzle_b32 v50, v47 offset:swizzle(SWAP,16)
	ds_swizzle_b32 v51, v11 offset:swizzle(SWAP,16)
	ds_swizzle_b32 v52, v14 offset:swizzle(SWAP,16)
	ds_swizzle_b32 v53, v15 offset:swizzle(SWAP,16)
	ds_swizzle_b32 v153, v18 offset:swizzle(SWAP,16)
	ds_swizzle_b32 v154, v6 offset:swizzle(SWAP,16)
	ds_swizzle_b32 v155, v8 offset:swizzle(SWAP,16)
	ds_swizzle_b32 v156, v12 offset:swizzle(SWAP,16)
	ds_swizzle_b32 v157, v46 offset:swizzle(SWAP,16)
	ds_swizzle_b32 v158, v2 offset:swizzle(SWAP,16)
	ds_swizzle_b32 v159, v10 offset:swizzle(SWAP,16)
	ds_swizzle_b32 v160, v9 offset:swizzle(SWAP,16)
	ds_swizzle_b32 v161, v13 offset:swizzle(SWAP,16)
	ds_swizzle_b32 v162, v5 offset:swizzle(SWAP,16)
	s_waitcnt lgkmcnt(0)
; __device__ __forceinline__ void merge16p(int (&a)[16], const int (&b)[16]) {
; #pragma unroll
;   for (int i = 0; i < 16; ++i) a[i] = max(a[i], b[15 - i]);
; #pragma unroll
;   for (int j = 8; j > 0; j >>= 1)
; #pragma unroll
;     for (int i = 0; i < 16; ++i) {
;       int l = i ^ j;
;       if (l > i) { CE1(a[i], a[l]); }
;     }
; }
; __device__ __forceinline__ void xmerge16p(int (&a)[16], int mask) {
;   int b[16];
; #pragma unroll
;   for (int i = 0; i < 16; ++i) b[i] = (mask == 16) ? __builtin_amdgcn_ds_swizzle(a[i], 0x401F) : __shfl_xor(a[i], 32);
;   merge16p(a, b);
; }
	v_max_i32_e32 v4, v4, v158
	v_max_i32_e32 v7, v7, v159
	v_max_i32_e32 v47, v47, v160
	v_max_i32_e32 v11, v11, v161
	v_max_i32_e32 v14, v14, v162
	v_max_i32_e32 v15, v15, v157
	v_max_i32_e32 v18, v18, v156
	v_max_i32_e32 v6, v6, v155
	v_max_i32_e32 v8, v8, v154
	v_max_i32_e32 v12, v12, v153
	v_max_i32_e32 v46, v46, v53
	v_max_i32_e32 v5, v5, v52
	v_max_i32_e32 v13, v13, v51
	v_max_i32_e32 v9, v9, v50
	v_max_i32_e32 v10, v10, v48
	v_max_i32_e32 v2, v2, v3
	v_max_i32_e32 v3, v4, v8
	v_min_i32_e32 v4, v4, v8
	v_max_i32_e32 v8, v7, v12
	v_min_i32_e32 v7, v7, v12
	v_max_i32_e32 v12, v47, v46
	v_min_i32_e32 v46, v47, v46
	v_max_i32_e32 v47, v11, v5
	v_min_i32_e32 v5, v11, v5
	v_max_i32_e32 v11, v14, v13
	v_min_i32_e32 v13, v14, v13
	v_max_i32_e32 v14, v15, v9
	v_min_i32_e32 v9, v15, v9
	v_max_i32_e32 v15, v18, v10
	v_min_i32_e32 v10, v18, v10
	v_max_i32_e32 v18, v6, v2
	v_min_i32_e32 v2, v6, v2
	v_max_i32_e32 v6, v3, v11
	v_min_i32_e32 v3, v3, v11
	v_max_i32_e32 v11, v8, v14
	v_min_i32_e32 v8, v8, v14
	v_max_i32_e32 v14, v12, v15
	v_min_i32_e32 v12, v12, v15
	v_max_i32_e32 v15, v47, v18
	v_min_i32_e32 v18, v47, v18
	v_max_i32_e32 v47, v4, v13
	v_min_i32_e32 v4, v4, v13
	v_max_i32_e32 v13, v7, v9
	v_min_i32_e32 v7, v7, v9
	v_max_i32_e32 v9, v46, v10
	v_min_i32_e32 v10, v46, v10
	v_max_i32_e32 v46, v5, v2
	v_min_i32_e32 v2, v5, v2
	v_max_i32_e32 v5, v6, v14
	v_min_i32_e32 v6, v6, v14
	v_max_i32_e32 v14, v11, v15
	v_min_i32_e32 v11, v11, v15
	v_max_i32_e32 v15, v3, v12
	v_min_i32_e32 v3, v3, v12
	v_max_i32_e32 v12, v8, v18
	v_min_i32_e32 v8, v8, v18
	v_max_i32_e32 v18, v47, v9
	v_min_i32_e32 v9, v47, v9
	v_max_i32_e32 v47, v13, v46
	v_min_i32_e32 v13, v13, v46
	v_max_i32_e32 v46, v4, v10
	v_min_i32_e32 v4, v4, v10
	v_max_i32_e32 v10, v7, v2
	v_min_i32_e32 v2, v7, v2
	v_max_i32_e32 v7, v5, v14
	v_min_i32_e32 v5, v5, v14
	v_max_i32_e32 v14, v6, v11
	v_min_i32_e32 v6, v6, v11
	v_max_i32_e32 v11, v15, v12
	v_min_i32_e32 v12, v15, v12
	v_max_i32_e32 v15, v3, v8
	v_min_i32_e32 v3, v3, v8
	v_max_i32_e32 v8, v18, v47
	v_min_i32_e32 v18, v18, v47
	v_max_i32_e32 v47, v9, v13
	v_min_i32_e32 v9, v9, v13
	v_max_i32_e32 v13, v46, v10
	v_min_i32_e32 v10, v46, v10
	v_max_i32_e32 v46, v4, v2
	v_min_i32_e32 v2, v4, v2
	ds_bpermute_b32 v4, v54, v7
	ds_bpermute_b32 v48, v54, v5
	ds_bpermute_b32 v50, v54, v14
	ds_bpermute_b32 v51, v54, v6
	ds_bpermute_b32 v52, v54, v11
	ds_bpermute_b32 v53, v54, v12
	ds_bpermute_b32 v153, v54, v15
	ds_bpermute_b32 v154, v54, v3
	ds_bpermute_b32 v155, v54, v8
	ds_bpermute_b32 v156, v54, v18
	ds_bpermute_b32 v157, v54, v47
	ds_bpermute_b32 v158, v54, v2
	ds_bpermute_b32 v159, v54, v46
	ds_bpermute_b32 v160, v54, v10
	ds_bpermute_b32 v161, v54, v13
	ds_bpermute_b32 v162, v54, v9
	s_waitcnt lgkmcnt(4)
	v_max_i32_e32 v7, v7, v158
	s_waitcnt lgkmcnt(3)
	v_max_i32_e32 v5, v5, v159
	s_waitcnt lgkmcnt(2)
	v_max_i32_e32 v14, v14, v160
	s_waitcnt lgkmcnt(1)
	v_max_i32_e32 v6, v6, v161
	s_waitcnt lgkmcnt(0)
; __device__ __forceinline__ void merge16p(int (&a)[16], const int (&b)[16]) {
; #pragma unroll
;   for (int i = 0; i < 16; ++i) a[i] = max(a[i], b[15 - i]);
; #pragma unroll
;   for (int j = 8; j > 0; j >>= 1)
; #pragma unroll
;     for (int i = 0; i < 16; ++i) {
;       int l = i ^ j;
;       if (l > i) { CE1(a[i], a[l]); }
;     }
; }
; __device__ void ph_score(const P& p, int* lds) {
;     ...
;       int idx4[4];
; #pragma unroll
;       for (int i = 0; i < 16; ++i) {
;         const int k = key_unmap(a[i]);
;         tv[half][i] = __int_as_float(k & ~0x7f);
;         if ((i >> 2) == 0) idx4[i & 3] = k & 0x7f;
;       }
; #pragma unroll
;       for (int i = 4; i < 16; ++i) {
;         const int k = key_unmap(a[i]) & 0x7f;
;         if ((i >> 2) == 1) idx4[i & 3] = (fq == 1) ? k : idx4[i & 3];
;         if ((i >> 2) == 2) idx4[i & 3] = (fq == 2) ? k : idx4[i & 3];
;         if ((i >> 2) == 3) idx4[i & 3] = (fq == 3) ? k : idx4[i & 3];
;       }
;       *(int4*)(myl + half * 16 + fq * 4) = make_int4(idx4[0], idx4[1], idx4[2], idx4[3]);
	v_max_i32_e32 v11, v11, v162
	v_max_i32_e32 v12, v12, v157
	v_max_i32_e32 v15, v15, v156
	v_max_i32_e32 v3, v3, v155
	v_max_i32_e32 v8, v8, v154
	v_max_i32_e32 v18, v18, v153
	v_max_i32_e32 v47, v47, v53
	v_max_i32_e32 v9, v9, v52
	v_max_i32_e32 v13, v13, v51
	v_max_i32_e32 v10, v10, v50
	v_max_i32_e32 v46, v46, v48
	v_max_i32_e32 v2, v2, v4
	v_max_i32_e32 v4, v7, v8
	v_min_i32_e32 v7, v7, v8
	v_max_i32_e32 v8, v5, v18
	v_min_i32_e32 v5, v5, v18
	v_max_i32_e32 v18, v14, v47
	v_min_i32_e32 v14, v14, v47
	v_max_i32_e32 v47, v6, v9
	v_min_i32_e32 v6, v6, v9
	v_max_i32_e32 v9, v11, v13
	v_min_i32_e32 v11, v11, v13
	v_max_i32_e32 v13, v12, v10
	v_min_i32_e32 v10, v12, v10
	v_max_i32_e32 v12, v15, v46
	v_min_i32_e32 v15, v15, v46
	v_max_i32_e32 v46, v3, v2
	v_min_i32_e32 v2, v3, v2
	v_max_i32_e32 v3, v4, v9
	v_min_i32_e32 v4, v4, v9
	v_max_i32_e32 v9, v8, v13
	v_min_i32_e32 v8, v8, v13
	v_max_i32_e32 v13, v18, v12
	v_min_i32_e32 v12, v18, v12
	v_max_i32_e32 v18, v47, v46
	v_min_i32_e32 v46, v47, v46
	v_max_i32_e32 v47, v7, v11
	v_min_i32_e32 v7, v7, v11
	v_max_i32_e32 v11, v5, v10
	v_min_i32_e32 v5, v5, v10
	v_max_i32_e32 v10, v14, v15
	v_min_i32_e32 v14, v14, v15
	v_max_i32_e32 v15, v6, v2
	v_min_i32_e32 v2, v6, v2
	v_max_i32_e32 v6, v3, v13
	v_min_i32_e32 v3, v3, v13
	v_max_i32_e32 v13, v9, v18
	v_min_i32_e32 v9, v9, v18
	v_max_i32_e32 v48, v4, v12
	v_min_i32_e32 v4, v4, v12
	v_max_i32_e32 v12, v8, v46
	v_min_i32_e32 v8, v8, v46
	v_max_i32_e32 v50, v47, v10
	v_min_i32_e32 v10, v47, v10
	v_max_i32_e32 v47, v11, v15
	v_min_i32_e32 v11, v11, v15
	v_max_i32_e32 v15, v7, v14
	v_min_i32_e32 v7, v7, v14
	v_max_i32_e32 v14, v5, v2
	v_min_i32_e32 v2, v5, v2
	v_max_i32_e32 v5, v6, v13
	v_min_i32_e32 v6, v6, v13
	v_max_i32_e32 v13, v3, v9
	v_min_i32_e32 v3, v3, v9
	v_max_i32_e32 v18, v48, v12
	v_min_i32_e32 v155, v48, v12
	v_max_i32_e32 v52, v4, v8
	v_min_i32_e32 v46, v4, v8
	v_max_i32_e32 v159, v50, v47
	v_min_i32_e32 v156, v50, v47
	v_max_i32_e32 v53, v10, v11
	v_min_i32_e32 v47, v10, v11
	v_max_i32_e32 v160, v15, v14
	v_min_i32_e32 v158, v15, v14
	v_max_i32_e32 v154, v7, v2
	v_min_i32_e32 v51, v7, v2
	v_ashrrev_i32_e32 v2, 31, v5
	v_and_b32_e32 v4, 0x7fffffff, v2
	v_bitop3_b32 v161, v2, v5, s75 bitop3:0x6c
	v_bitop3_b32 v2, v4, s80, v5 bitop3:0x48
	v_ashrrev_i32_e32 v4, 31, v6
	v_and_b32_e32 v5, 0x7fffffff, v4
	v_bitop3_b32 v157, v4, v6, s75 bitop3:0x6c
	v_bitop3_b32 v4, v5, s80, v6 bitop3:0x48
	v_ashrrev_i32_e32 v5, 31, v13
	v_and_b32_e32 v6, 0x7fffffff, v5
	v_bitop3_b32 v153, v5, v13, s75 bitop3:0x6c
	v_bitop3_b32 v5, v6, s80, v13 bitop3:0x48
	v_ashrrev_i32_e32 v6, 31, v3
	v_and_b32_e32 v7, 0x7fffffff, v6
	v_bitop3_b32 v50, v6, v3, s75 bitop3:0x6c
	v_ashrrev_i32_e32 v6, 31, v18
	v_bitop3_b32 v6, v6, s80, v18 bitop3:0x48
	v_cndmask_b32_e64 v2, v2, v6, s[6:7]
	v_ashrrev_i32_e32 v6, 31, v155
	v_bitop3_b32 v6, v6, s80, v155 bitop3:0x48
	v_cndmask_b32_e64 v4, v4, v6, s[6:7]
	v_ashrrev_i32_e32 v6, 31, v52
	v_bitop3_b32 v6, v6, s80, v52 bitop3:0x48
	v_cndmask_b32_e64 v5, v5, v6, s[6:7]
	v_ashrrev_i32_e32 v6, 31, v46
	v_bitop3_b32 v3, v7, s80, v3 bitop3:0x48
	v_bitop3_b32 v6, v6, s80, v46 bitop3:0x48
	v_cndmask_b32_e64 v3, v3, v6, s[6:7]
	v_ashrrev_i32_e32 v6, 31, v159
	v_bitop3_b32 v6, v6, s80, v159 bitop3:0x48
	v_cndmask_b32_e64 v2, v2, v6, s[4:5]
	v_ashrrev_i32_e32 v6, 31, v156
	v_bitop3_b32 v6, v6, s80, v156 bitop3:0x48
	v_cndmask_b32_e64 v4, v4, v6, s[4:5]
	v_ashrrev_i32_e32 v6, 31, v53
	v_bitop3_b32 v6, v6, s80, v53 bitop3:0x48
	v_cndmask_b32_e64 v5, v5, v6, s[4:5]
	v_ashrrev_i32_e32 v6, 31, v47
	v_bitop3_b32 v6, v6, s80, v47 bitop3:0x48
	v_cndmask_b32_e64 v6, v3, v6, s[4:5]
	v_ashrrev_i32_e32 v3, 31, v160
	v_bitop3_b32 v3, v3, s80, v160 bitop3:0x48
	v_cndmask_b32_e64 v2, v2, v3, s[0:1]
	v_ashrrev_i32_e32 v3, 31, v158
	v_bitop3_b32 v3, v3, s80, v158 bitop3:0x48
	v_cndmask_b32_e64 v3, v4, v3, s[0:1]
	v_ashrrev_i32_e32 v4, 31, v154
	v_bitop3_b32 v4, v4, s80, v154 bitop3:0x48
	v_cndmask_b32_e64 v4, v5, v4, s[0:1]
	v_ashrrev_i32_e32 v5, 31, v51
	v_bitop3_b32 v5, v5, s80, v51 bitop3:0x48
	v_lshl_add_u64 v[14:15], v[24:25], 0, s[70:71]
	v_cndmask_b32_e64 v5, v6, v5, s[0:1]


; __device__ void ph_score(const P& p, int* lds) {
;     ...
;         bf16x8 qf = *(const bf16x8*)(Qb + tok * 2048 + h * 256 + half * 128 + ks * 32 + fq * 8);
;     ...
;       *(int4*)(myl + half * 16 + fq * 4) = make_int4(idx4[0], idx4[1], idx4[2], idx4[3]);
	ds_write_b128 v150, v[2:5]
	global_load_dwordx4 v[2:5], v[0:1], off offset:256


; __device__ __forceinline__ f32x4 mfma16(bf16x8 a, bf16x8 b, f32x4 c) { return __builtin_amdgcn_mfma_f32_16x16x32_bf16(a, b, c, 0, 0, 0); }
; __device__ void ph_score(const P& p, int* lds) {
;     ...
;       for (int ks = 0; ks < 4; ++ks) {
;         bf16x8 qf = *(const bf16x8*)(Qb + tok * 2048 + h * 256 + half * 128 + ks * 32 + fq * 8);
; #pragma unroll
;         for (int mt = 0; mt < 8; ++mt) {
;           bf16x8 kf = *(const bf16x8*)(Kb + (mt * 16 + fr) * 128 + ks * 32 + fq * 8);
;           sc[mt] = mfma16(kf, qf, sc[mt]);
;         }
;       }
	ds_read_b128 v[6:9], v224 offset:0
	v_lshl_add_u64 v[192:193], v[14:15], 0, 64


; __device__ __forceinline__ f32x4 mfma16(bf16x8 a, bf16x8 b, f32x4 c) { return __builtin_amdgcn_mfma_f32_16x16x32_bf16(a, b, c, 0, 0, 0); }
; __device__ void ph_score(const P& p, int* lds) {
;     ...
;       for (int ks = 0; ks < 4; ++ks) {
;         bf16x8 qf = *(const bf16x8*)(Qb + tok * 2048 + h * 256 + half * 128 + ks * 32 + fq * 8);
; #pragma unroll
;         for (int mt = 0; mt < 8; ++mt) {
;           bf16x8 kf = *(const bf16x8*)(Kb + (mt * 16 + fr) * 128 + ks * 32 + fq * 8);
;           sc[mt] = mfma16(kf, qf, sc[mt]);
;         }
;       }
	ds_read_b128 v[10:13], v224 offset:4352
	v_lshl_add_u64 v[194:195], v[14:15], 0, s[76:77]


; __device__ __forceinline__ f32x4 mfma16(bf16x8 a, bf16x8 b, f32x4 c) { return __builtin_amdgcn_mfma_f32_16x16x32_bf16(a, b, c, 0, 0, 0); }
; __device__ void ph_score(const P& p, int* lds) {
;     ...
;       for (int ks = 0; ks < 4; ++ks) {
;         bf16x8 qf = *(const bf16x8*)(Qb + tok * 2048 + h * 256 + half * 128 + ks * 32 + fq * 8);
; #pragma unroll
;         for (int mt = 0; mt < 8; ++mt) {
;           bf16x8 kf = *(const bf16x8*)(Kb + (mt * 16 + fr) * 128 + ks * 32 + fq * 8);
;           sc[mt] = mfma16(kf, qf, sc[mt]);
;         }
;       }
;     ...
; #pragma unroll
;       for (int i = 0; i < 16; ++i) {
;         const int k = key_unmap(a[i]);
;         tv[half][i] = __int_as_float(k & ~0x7f);
;         if ((i >> 2) == 0) idx4[i & 3] = k & 0x7f;
	ds_read_b128 v[162:165], v224 offset:8704
	v_cmp_gt_i32_e64 s[26:27], 0, v18


; __device__ __forceinline__ f32x4 mfma16(bf16x8 a, bf16x8 b, f32x4 c) { return __builtin_amdgcn_mfma_f32_16x16x32_bf16(a, b, c, 0, 0, 0); }
; __device__ void ph_score(const P& p, int* lds) {
;     ...
;       for (int ks = 0; ks < 4; ++ks) {
;         bf16x8 qf = *(const bf16x8*)(Qb + tok * 2048 + h * 256 + half * 128 + ks * 32 + fq * 8);
; #pragma unroll
;         for (int mt = 0; mt < 8; ++mt) {
;           bf16x8 kf = *(const bf16x8*)(Kb + (mt * 16 + fr) * 128 + ks * 32 + fq * 8);
;           sc[mt] = mfma16(kf, qf, sc[mt]);
;         }
;       }
;     ...
; #pragma unroll
;       for (int i = 0; i < 16; ++i) {
;         const int k = key_unmap(a[i]);
;         tv[half][i] = __int_as_float(k & ~0x7f);
;         if ((i >> 2) == 0) idx4[i & 3] = k & 0x7f;
	ds_read_b128 v[166:169], v224 offset:13056
	v_cmp_gt_i32_e64 s[20:21], 0, v155


; __device__ __forceinline__ f32x4 mfma16(bf16x8 a, bf16x8 b, f32x4 c) { return __builtin_amdgcn_mfma_f32_16x16x32_bf16(a, b, c, 0, 0, 0); }
; __device__ void ph_score(const P& p, int* lds) {
;     ...
;       for (int ks = 0; ks < 4; ++ks) {
;         bf16x8 qf = *(const bf16x8*)(Qb + tok * 2048 + h * 256 + half * 128 + ks * 32 + fq * 8);
; #pragma unroll
;         for (int mt = 0; mt < 8; ++mt) {
;           bf16x8 kf = *(const bf16x8*)(Kb + (mt * 16 + fr) * 128 + ks * 32 + fq * 8);
;           sc[mt] = mfma16(kf, qf, sc[mt]);
;         }
;       }
;     ...
; #pragma unroll
;       for (int i = 0; i < 16; ++i) {
;         const int k = key_unmap(a[i]);
;         tv[half][i] = __int_as_float(k & ~0x7f);
;         if ((i >> 2) == 0) idx4[i & 3] = k & 0x7f;
	ds_read_b128 v[170:173], v224 offset:17408
	v_cmp_gt_i32_e64 s[14:15], 0, v52


; __device__ __forceinline__ f32x4 mfma16(bf16x8 a, bf16x8 b, f32x4 c) { return __builtin_amdgcn_mfma_f32_16x16x32_bf16(a, b, c, 0, 0, 0); }
; __device__ void ph_score(const P& p, int* lds) {
;     ...
;       for (int ks = 0; ks < 4; ++ks) {
;         bf16x8 qf = *(const bf16x8*)(Qb + tok * 2048 + h * 256 + half * 128 + ks * 32 + fq * 8);
; #pragma unroll
;         for (int mt = 0; mt < 8; ++mt) {
;           bf16x8 kf = *(const bf16x8*)(Kb + (mt * 16 + fr) * 128 + ks * 32 + fq * 8);
;           sc[mt] = mfma16(kf, qf, sc[mt]);
;         }
;       }
;     ...
; #pragma unroll
;       for (int i = 0; i < 16; ++i) {
;         const int k = key_unmap(a[i]);
;         tv[half][i] = __int_as_float(k & ~0x7f);
;         if ((i >> 2) == 0) idx4[i & 3] = k & 0x7f;
	ds_read_b128 v[174:177], v224 offset:21760
	v_cmp_gt_i32_e32 vcc, 0, v46


; __device__ __forceinline__ f32x4 mfma16(bf16x8 a, bf16x8 b, f32x4 c) { return __builtin_amdgcn_mfma_f32_16x16x32_bf16(a, b, c, 0, 0, 0); }
; __device__ void ph_score(const P& p, int* lds) {
;     ...
;       for (int ks = 0; ks < 4; ++ks) {
;         bf16x8 qf = *(const bf16x8*)(Qb + tok * 2048 + h * 256 + half * 128 + ks * 32 + fq * 8);
; #pragma unroll
;         for (int mt = 0; mt < 8; ++mt) {
;           bf16x8 kf = *(const bf16x8*)(Kb + (mt * 16 + fr) * 128 + ks * 32 + fq * 8);
;           sc[mt] = mfma16(kf, qf, sc[mt]);
;         }
;       }
;     ...
; #pragma unroll
;       for (int i = 0; i < 16; ++i) {
;         const int k = key_unmap(a[i]);
;         tv[half][i] = __int_as_float(k & ~0x7f);
;         if ((i >> 2) == 0) idx4[i & 3] = k & 0x7f;
	ds_read_b128 v[178:181], v224 offset:26112
	v_cmp_gt_i32_e64 s[28:29], 0, v159


; __device__ __forceinline__ f32x4 mfma16(bf16x8 a, bf16x8 b, f32x4 c) { return __builtin_amdgcn_mfma_f32_16x16x32_bf16(a, b, c, 0, 0, 0); }
; __device__ void ph_score(const P& p, int* lds) {
;     ...
;       for (int ks = 0; ks < 4; ++ks) {
;         bf16x8 qf = *(const bf16x8*)(Qb + tok * 2048 + h * 256 + half * 128 + ks * 32 + fq * 8);
; #pragma unroll
;         for (int mt = 0; mt < 8; ++mt) {
;           bf16x8 kf = *(const bf16x8*)(Kb + (mt * 16 + fr) * 128 + ks * 32 + fq * 8);
;           sc[mt] = mfma16(kf, qf, sc[mt]);
;         }
;       }
;     ...
; #pragma unroll
;       for (int i = 0; i < 16; ++i) {
;         const int k = key_unmap(a[i]);
;         tv[half][i] = __int_as_float(k & ~0x7f);
;         if ((i >> 2) == 0) idx4[i & 3] = k & 0x7f;
	ds_read_b128 v[182:185], v224 offset:30464
	v_cmp_gt_i32_e64 s[22:23], 0, v156
	v_cmp_gt_i32_e64 s[16:17], 0, v53
	v_cmp_gt_i32_e64 s[10:11], 0, v47
	v_cmp_gt_i32_e64 s[30:31], 0, v160
	v_cmp_gt_i32_e64 s[24:25], 0, v158
	v_cmp_gt_i32_e64 s[18:19], 0, v154
	v_cmp_gt_i32_e64 s[12:13], 0, v51
	s_waitcnt vmcnt(0) lgkmcnt(0)
	v_mfma_f32_16x16x32_bf16 v[162:165], v[162:165], v[2:5], 0


; __device__ __forceinline__ f32x4 mfma16(bf16x8 a, bf16x8 b, f32x4 c) { return __builtin_amdgcn_mfma_f32_16x16x32_bf16(a, b, c, 0, 0, 0); }
; __device__ void ph_score(const P& p, int* lds) {
;     ...
;       for (int ks = 0; ks < 4; ++ks) {
;         bf16x8 qf = *(const bf16x8*)(Qb + tok * 2048 + h * 256 + half * 128 + ks * 32 + fq * 8);
; #pragma unroll
;         for (int mt = 0; mt < 8; ++mt) {
;           bf16x8 kf = *(const bf16x8*)(Kb + (mt * 16 + fr) * 128 + ks * 32 + fq * 8);
;           sc[mt] = mfma16(kf, qf, sc[mt]);
;         }
;       }
	ds_read_b128 v[186:189], v224 offset:64
	v_mfma_f32_16x16x32_bf16 v[6:9], v[6:9], v[2:5], 0
	v_mfma_f32_16x16x32_bf16 v[10:13], v[10:13], v[2:5], 0
	s_waitcnt vmcnt(0) lgkmcnt(0)
	v_mfma_f32_16x16x32_bf16 v[166:169], v[166:169], v[2:5], 0
	s_waitcnt vmcnt(0) lgkmcnt(0)
	v_mfma_f32_16x16x32_bf16 v[170:173], v[170:173], v[2:5], 0
	s_waitcnt vmcnt(0) lgkmcnt(0)
	v_mfma_f32_16x16x32_bf16 v[174:177], v[174:177], v[2:5], 0
	s_waitcnt vmcnt(0) lgkmcnt(0)
	v_mfma_f32_16x16x32_bf16 v[178:181], v[178:181], v[2:5], 0
	s_waitcnt vmcnt(0) lgkmcnt(0)
	v_mfma_f32_16x16x32_bf16 v[2:5], v[182:185], v[2:5], 0
	global_load_dwordx4 v[182:185], v[0:1], off offset:320
	s_waitcnt vmcnt(0) lgkmcnt(0)
	v_mfma_f32_16x16x32_bf16 v[6:9], v[186:189], v[182:185], v[6:9]


; __device__ __forceinline__ f32x4 mfma16(bf16x8 a, bf16x8 b, f32x4 c) { return __builtin_amdgcn_mfma_f32_16x16x32_bf16(a, b, c, 0, 0, 0); }
; __device__ void ph_score(const P& p, int* lds) {
;     ...
;       for (int ks = 0; ks < 4; ++ks) {
;         bf16x8 qf = *(const bf16x8*)(Qb + tok * 2048 + h * 256 + half * 128 + ks * 32 + fq * 8);
; #pragma unroll
;         for (int mt = 0; mt < 8; ++mt) {
;           bf16x8 kf = *(const bf16x8*)(Kb + (mt * 16 + fr) * 128 + ks * 32 + fq * 8);
;           sc[mt] = mfma16(kf, qf, sc[mt]);
;         }
;       }
	ds_read_b128 v[186:189], v224 offset:4416
	s_waitcnt vmcnt(0) lgkmcnt(0)
	v_mfma_f32_16x16x32_bf16 v[10:13], v[186:189], v[182:185], v[10:13]


; __device__ __forceinline__ f32x4 mfma16(bf16x8 a, bf16x8 b, f32x4 c) { return __builtin_amdgcn_mfma_f32_16x16x32_bf16(a, b, c, 0, 0, 0); }
; __device__ void ph_score(const P& p, int* lds) {
;     ...
;       for (int ks = 0; ks < 4; ++ks) {
;         bf16x8 qf = *(const bf16x8*)(Qb + tok * 2048 + h * 256 + half * 128 + ks * 32 + fq * 8);
; #pragma unroll
;         for (int mt = 0; mt < 8; ++mt) {
;           bf16x8 kf = *(const bf16x8*)(Kb + (mt * 16 + fr) * 128 + ks * 32 + fq * 8);
;           sc[mt] = mfma16(kf, qf, sc[mt]);
;         }
;       }
	ds_read_b128 v[186:189], v224 offset:8768
	s_waitcnt vmcnt(0) lgkmcnt(0)
	v_mfma_f32_16x16x32_bf16 v[162:165], v[186:189], v[182:185], v[162:165]


; __device__ __forceinline__ f32x4 mfma16(bf16x8 a, bf16x8 b, f32x4 c) { return __builtin_amdgcn_mfma_f32_16x16x32_bf16(a, b, c, 0, 0, 0); }
; __device__ void ph_score(const P& p, int* lds) {
;     ...
;       for (int ks = 0; ks < 4; ++ks) {
;         bf16x8 qf = *(const bf16x8*)(Qb + tok * 2048 + h * 256 + half * 128 + ks * 32 + fq * 8);
; #pragma unroll
;         for (int mt = 0; mt < 8; ++mt) {
;           bf16x8 kf = *(const bf16x8*)(Kb + (mt * 16 + fr) * 128 + ks * 32 + fq * 8);
;           sc[mt] = mfma16(kf, qf, sc[mt]);
;         }
;       }
	ds_read_b128 v[186:189], v224 offset:13120
	s_waitcnt vmcnt(0) lgkmcnt(0)
	v_mfma_f32_16x16x32_bf16 v[166:169], v[186:189], v[182:185], v[166:169]


; __device__ __forceinline__ f32x4 mfma16(bf16x8 a, bf16x8 b, f32x4 c) { return __builtin_amdgcn_mfma_f32_16x16x32_bf16(a, b, c, 0, 0, 0); }
; __device__ void ph_score(const P& p, int* lds) {
;     ...
;       for (int ks = 0; ks < 4; ++ks) {
;         bf16x8 qf = *(const bf16x8*)(Qb + tok * 2048 + h * 256 + half * 128 + ks * 32 + fq * 8);
; #pragma unroll
;         for (int mt = 0; mt < 8; ++mt) {
;           bf16x8 kf = *(const bf16x8*)(Kb + (mt * 16 + fr) * 128 + ks * 32 + fq * 8);
;           sc[mt] = mfma16(kf, qf, sc[mt]);
;         }
;       }
	ds_read_b128 v[186:189], v224 offset:17472
	s_waitcnt vmcnt(0) lgkmcnt(0)
	v_mfma_f32_16x16x32_bf16 v[170:173], v[186:189], v[182:185], v[170:173]


; __device__ __forceinline__ f32x4 mfma16(bf16x8 a, bf16x8 b, f32x4 c) { return __builtin_amdgcn_mfma_f32_16x16x32_bf16(a, b, c, 0, 0, 0); }
; __device__ void ph_score(const P& p, int* lds) {
;     ...
;       for (int ks = 0; ks < 4; ++ks) {
;         bf16x8 qf = *(const bf16x8*)(Qb + tok * 2048 + h * 256 + half * 128 + ks * 32 + fq * 8);
; #pragma unroll
;         for (int mt = 0; mt < 8; ++mt) {
;           bf16x8 kf = *(const bf16x8*)(Kb + (mt * 16 + fr) * 128 + ks * 32 + fq * 8);
;           sc[mt] = mfma16(kf, qf, sc[mt]);
;         }
;       }
	ds_read_b128 v[186:189], v224 offset:21824
	s_waitcnt vmcnt(0) lgkmcnt(0)
	v_mfma_f32_16x16x32_bf16 v[174:177], v[186:189], v[182:185], v[174:177]


; __device__ __forceinline__ f32x4 mfma16(bf16x8 a, bf16x8 b, f32x4 c) { return __builtin_amdgcn_mfma_f32_16x16x32_bf16(a, b, c, 0, 0, 0); }
; __device__ void ph_score(const P& p, int* lds) {
;     ...
;       for (int ks = 0; ks < 4; ++ks) {
;         bf16x8 qf = *(const bf16x8*)(Qb + tok * 2048 + h * 256 + half * 128 + ks * 32 + fq * 8);
; #pragma unroll
;         for (int mt = 0; mt < 8; ++mt) {
;           bf16x8 kf = *(const bf16x8*)(Kb + (mt * 16 + fr) * 128 + ks * 32 + fq * 8);
;           sc[mt] = mfma16(kf, qf, sc[mt]);
;         }
;       }
	ds_read_b128 v[186:189], v224 offset:26176
	s_waitcnt vmcnt(0) lgkmcnt(0)
	v_mfma_f32_16x16x32_bf16 v[178:181], v[186:189], v[182:185], v[178:181]


; __device__ __forceinline__ f32x4 mfma16(bf16x8 a, bf16x8 b, f32x4 c) { return __builtin_amdgcn_mfma_f32_16x16x32_bf16(a, b, c, 0, 0, 0); }
; __device__ void ph_score(const P& p, int* lds) {
;     ...
;       for (int ks = 0; ks < 4; ++ks) {
;         bf16x8 qf = *(const bf16x8*)(Qb + tok * 2048 + h * 256 + half * 128 + ks * 32 + fq * 8);
; #pragma unroll
;         for (int mt = 0; mt < 8; ++mt) {
;           bf16x8 kf = *(const bf16x8*)(Kb + (mt * 16 + fr) * 128 + ks * 32 + fq * 8);
;           sc[mt] = mfma16(kf, qf, sc[mt]);
;         }
;       }
	ds_read_b128 v[186:189], v224 offset:30528
	v_lshl_add_u64 v[192:193], v[14:15], 0, s[72:73]
	s_waitcnt vmcnt(0) lgkmcnt(0)
	v_mfma_f32_16x16x32_bf16 v[2:5], v[186:189], v[182:185], v[2:5]
	global_load_dwordx4 v[182:185], v[0:1], off offset:384


; __device__ __forceinline__ f32x4 mfma16(bf16x8 a, bf16x8 b, f32x4 c) { return __builtin_amdgcn_mfma_f32_16x16x32_bf16(a, b, c, 0, 0, 0); }
; __device__ void ph_score(const P& p, int* lds) {
;     ...
;       for (int ks = 0; ks < 4; ++ks) {
;         bf16x8 qf = *(const bf16x8*)(Qb + tok * 2048 + h * 256 + half * 128 + ks * 32 + fq * 8);
; #pragma unroll
;         for (int mt = 0; mt < 8; ++mt) {
;           bf16x8 kf = *(const bf16x8*)(Kb + (mt * 16 + fr) * 128 + ks * 32 + fq * 8);
;           sc[mt] = mfma16(kf, qf, sc[mt]);
;         }
;       }
	ds_read_b128 v[186:189], v224 offset:128
	s_waitcnt vmcnt(0) lgkmcnt(0)
	v_mfma_f32_16x16x32_bf16 v[6:9], v[186:189], v[182:185], v[6:9]


; __device__ __forceinline__ f32x4 mfma16(bf16x8 a, bf16x8 b, f32x4 c) { return __builtin_amdgcn_mfma_f32_16x16x32_bf16(a, b, c, 0, 0, 0); }
; __device__ void ph_score(const P& p, int* lds) {
;     ...
;       for (int ks = 0; ks < 4; ++ks) {
;         bf16x8 qf = *(const bf16x8*)(Qb + tok * 2048 + h * 256 + half * 128 + ks * 32 + fq * 8);
; #pragma unroll
;         for (int mt = 0; mt < 8; ++mt) {
;           bf16x8 kf = *(const bf16x8*)(Kb + (mt * 16 + fr) * 128 + ks * 32 + fq * 8);
;           sc[mt] = mfma16(kf, qf, sc[mt]);
;         }
;       }
	ds_read_b128 v[186:189], v224 offset:4480
	s_waitcnt vmcnt(0) lgkmcnt(0)
	v_mfma_f32_16x16x32_bf16 v[10:13], v[186:189], v[182:185], v[10:13]


; __device__ __forceinline__ f32x4 mfma16(bf16x8 a, bf16x8 b, f32x4 c) { return __builtin_amdgcn_mfma_f32_16x16x32_bf16(a, b, c, 0, 0, 0); }
; __device__ void ph_score(const P& p, int* lds) {
;     ...
;       for (int ks = 0; ks < 4; ++ks) {
;         bf16x8 qf = *(const bf16x8*)(Qb + tok * 2048 + h * 256 + half * 128 + ks * 32 + fq * 8);
; #pragma unroll
;         for (int mt = 0; mt < 8; ++mt) {
;           bf16x8 kf = *(const bf16x8*)(Kb + (mt * 16 + fr) * 128 + ks * 32 + fq * 8);
;           sc[mt] = mfma16(kf, qf, sc[mt]);
;         }
;       }
	ds_read_b128 v[186:189], v224 offset:8832
	s_waitcnt vmcnt(0) lgkmcnt(0)
	v_mfma_f32_16x16x32_bf16 v[162:165], v[186:189], v[182:185], v[162:165]


; __device__ __forceinline__ f32x4 mfma16(bf16x8 a, bf16x8 b, f32x4 c) { return __builtin_amdgcn_mfma_f32_16x16x32_bf16(a, b, c, 0, 0, 0); }
; __device__ void ph_score(const P& p, int* lds) {
;     ...
;       for (int ks = 0; ks < 4; ++ks) {
;         bf16x8 qf = *(const bf16x8*)(Qb + tok * 2048 + h * 256 + half * 128 + ks * 32 + fq * 8);
; #pragma unroll
;         for (int mt = 0; mt < 8; ++mt) {
;           bf16x8 kf = *(const bf16x8*)(Kb + (mt * 16 + fr) * 128 + ks * 32 + fq * 8);
;           sc[mt] = mfma16(kf, qf, sc[mt]);
;         }
;       }
	ds_read_b128 v[186:189], v224 offset:13184
	s_waitcnt vmcnt(0) lgkmcnt(0)
	v_mfma_f32_16x16x32_bf16 v[166:169], v[186:189], v[182:185], v[166:169]


; __device__ __forceinline__ f32x4 mfma16(bf16x8 a, bf16x8 b, f32x4 c) { return __builtin_amdgcn_mfma_f32_16x16x32_bf16(a, b, c, 0, 0, 0); }
; __device__ void ph_score(const P& p, int* lds) {
;     ...
;       for (int ks = 0; ks < 4; ++ks) {
;         bf16x8 qf = *(const bf16x8*)(Qb + tok * 2048 + h * 256 + half * 128 + ks * 32 + fq * 8);
; #pragma unroll
;         for (int mt = 0; mt < 8; ++mt) {
;           bf16x8 kf = *(const bf16x8*)(Kb + (mt * 16 + fr) * 128 + ks * 32 + fq * 8);
;           sc[mt] = mfma16(kf, qf, sc[mt]);
;         }
;       }
	ds_read_b128 v[186:189], v224 offset:17536
	s_waitcnt vmcnt(0) lgkmcnt(0)
	v_mfma_f32_16x16x32_bf16 v[170:173], v[186:189], v[182:185], v[170:173]


; __device__ __forceinline__ f32x4 mfma16(bf16x8 a, bf16x8 b, f32x4 c) { return __builtin_amdgcn_mfma_f32_16x16x32_bf16(a, b, c, 0, 0, 0); }
; __device__ void ph_score(const P& p, int* lds) {
;     ...
;       for (int ks = 0; ks < 4; ++ks) {
;         bf16x8 qf = *(const bf16x8*)(Qb + tok * 2048 + h * 256 + half * 128 + ks * 32 + fq * 8);
; #pragma unroll
;         for (int mt = 0; mt < 8; ++mt) {
;           bf16x8 kf = *(const bf16x8*)(Kb + (mt * 16 + fr) * 128 + ks * 32 + fq * 8);
;           sc[mt] = mfma16(kf, qf, sc[mt]);
;         }
;       }
	ds_read_b128 v[186:189], v224 offset:21888
	s_waitcnt vmcnt(0) lgkmcnt(0)
	v_mfma_f32_16x16x32_bf16 v[174:177], v[186:189], v[182:185], v[174:177]


; __device__ __forceinline__ f32x4 mfma16(bf16x8 a, bf16x8 b, f32x4 c) { return __builtin_amdgcn_mfma_f32_16x16x32_bf16(a, b, c, 0, 0, 0); }
; __device__ void ph_score(const P& p, int* lds) {
;     ...
;       for (int ks = 0; ks < 4; ++ks) {
;         bf16x8 qf = *(const bf16x8*)(Qb + tok * 2048 + h * 256 + half * 128 + ks * 32 + fq * 8);
; #pragma unroll
;         for (int mt = 0; mt < 8; ++mt) {
;           bf16x8 kf = *(const bf16x8*)(Kb + (mt * 16 + fr) * 128 + ks * 32 + fq * 8);
;           sc[mt] = mfma16(kf, qf, sc[mt]);
;         }
;       }
	ds_read_b128 v[186:189], v224 offset:26240
	s_waitcnt vmcnt(0) lgkmcnt(0)
	v_mfma_f32_16x16x32_bf16 v[178:181], v[186:189], v[182:185], v[178:181]


; __device__ __forceinline__ f32x4 mfma16(bf16x8 a, bf16x8 b, f32x4 c) { return __builtin_amdgcn_mfma_f32_16x16x32_bf16(a, b, c, 0, 0, 0); }
; __device__ void ph_score(const P& p, int* lds) {
;     ...
;       for (int ks = 0; ks < 4; ++ks) {
;         bf16x8 qf = *(const bf16x8*)(Qb + tok * 2048 + h * 256 + half * 128 + ks * 32 + fq * 8);
; #pragma unroll
;         for (int mt = 0; mt < 8; ++mt) {
;           bf16x8 kf = *(const bf16x8*)(Kb + (mt * 16 + fr) * 128 + ks * 32 + fq * 8);
;           sc[mt] = mfma16(kf, qf, sc[mt]);
;         }
;       }
	ds_read_b128 v[186:189], v224 offset:30592
	s_waitcnt vmcnt(0) lgkmcnt(0)
	v_mfma_f32_16x16x32_bf16 v[182:185], v[186:189], v[182:185], v[2:5]
	global_load_dwordx4 v[186:189], v[0:1], off offset:448
	s_nop 1


; __device__ __forceinline__ f32x4 mfma16(bf16x8 a, bf16x8 b, f32x4 c) { return __builtin_amdgcn_mfma_f32_16x16x32_bf16(a, b, c, 0, 0, 0); }
; __device__ void ph_score(const P& p, int* lds) {
;     ...
;       for (int ks = 0; ks < 4; ++ks) {
;         bf16x8 qf = *(const bf16x8*)(Qb + tok * 2048 + h * 256 + half * 128 + ks * 32 + fq * 8);
; #pragma unroll
;         for (int mt = 0; mt < 8; ++mt) {
;           bf16x8 kf = *(const bf16x8*)(Kb + (mt * 16 + fr) * 128 + ks * 32 + fq * 8);
;           sc[mt] = mfma16(kf, qf, sc[mt]);
;         }
;       }
;       int a[16], b[16];
; #pragma unroll
;       for (int mt = 0; mt < 4; ++mt)
; #pragma unroll
;         for (int r = 0; r < 4; ++r) {
;           a[mt * 4 + r] = key_pack(sc[mt][r], mt * 16 + fq * 4 + r, 0x7f);
;           b[mt * 4 + r] = key_pack(sc[mt + 4][r], (mt + 4) * 16 + fq * 4 + r, 0x7f);
;         }
	ds_read_b128 v[0:3], v224 offset:192
	s_waitcnt vmcnt(0) lgkmcnt(0)
	v_mfma_f32_16x16x32_bf16 v[190:193], v[0:3], v[186:189], v[6:9]
	s_nop 0
	s_nop 0
	s_nop 0
	s_nop 0
	ds_read_b128 v[0:3], v224 offset:4544
	s_nop 0
	s_nop 0
	s_nop 3
	v_and_b32_e32 v48, 0xffffff80, v190
	s_waitcnt vmcnt(0) lgkmcnt(0)
	v_mfma_f32_16x16x32_bf16 v[12:15], v[0:3], v[186:189], v[10:13]


; __device__ __forceinline__ f32x4 mfma16(bf16x8 a, bf16x8 b, f32x4 c) { return __builtin_amdgcn_mfma_f32_16x16x32_bf16(a, b, c, 0, 0, 0); }
; __device__ void ph_score(const P& p, int* lds) {
;     ...
;       for (int ks = 0; ks < 4; ++ks) {
;         bf16x8 qf = *(const bf16x8*)(Qb + tok * 2048 + h * 256 + half * 128 + ks * 32 + fq * 8);
; #pragma unroll
;         for (int mt = 0; mt < 8; ++mt) {
;           bf16x8 kf = *(const bf16x8*)(Kb + (mt * 16 + fr) * 128 + ks * 32 + fq * 8);
;           sc[mt] = mfma16(kf, qf, sc[mt]);
;         }
;       }
	ds_read_b128 v[0:3], v224 offset:8896
	s_nop 0


; __device__ __forceinline__ f32x4 mfma16(bf16x8 a, bf16x8 b, f32x4 c) { return __builtin_amdgcn_mfma_f32_16x16x32_bf16(a, b, c, 0, 0, 0); }
; __device__ void ph_score(const P& p, int* lds) {
;     ...
;       for (int ks = 0; ks < 4; ++ks) {
;         bf16x8 qf = *(const bf16x8*)(Qb + tok * 2048 + h * 256 + half * 128 + ks * 32 + fq * 8);
; #pragma unroll
;         for (int mt = 0; mt < 8; ++mt) {
;           bf16x8 kf = *(const bf16x8*)(Kb + (mt * 16 + fr) * 128 + ks * 32 + fq * 8);
;           sc[mt] = mfma16(kf, qf, sc[mt]);
;         }
;       }
	ds_read_b128 v[8:11], v224 offset:17600
	s_waitcnt vmcnt(0) lgkmcnt(0)
	v_mfma_f32_16x16x32_bf16 v[4:7], v[0:3], v[186:189], v[162:165]


; __device__ __forceinline__ f32x4 mfma16(bf16x8 a, bf16x8 b, f32x4 c) { return __builtin_amdgcn_mfma_f32_16x16x32_bf16(a, b, c, 0, 0, 0); }
; __device__ void ph_score(const P& p, int* lds) {
;     ...
;       for (int ks = 0; ks < 4; ++ks) {
;         bf16x8 qf = *(const bf16x8*)(Qb + tok * 2048 + h * 256 + half * 128 + ks * 32 + fq * 8);
; #pragma unroll
;         for (int mt = 0; mt < 8; ++mt) {
;           bf16x8 kf = *(const bf16x8*)(Kb + (mt * 16 + fr) * 128 + ks * 32 + fq * 8);
;           sc[mt] = mfma16(kf, qf, sc[mt]);
;         }
;       }
	ds_read_b128 v[0:3], v224 offset:13248
	s_waitcnt vmcnt(0) lgkmcnt(0)
	v_mfma_f32_16x16x32_bf16 v[162:165], v[8:11], v[186:189], v[170:173]


; __device__ __forceinline__ f32x4 mfma16(bf16x8 a, bf16x8 b, f32x4 c) { return __builtin_amdgcn_mfma_f32_16x16x32_bf16(a, b, c, 0, 0, 0); }
; __device__ void ph_score(const P& p, int* lds) {
;     ...
;       for (int ks = 0; ks < 4; ++ks) {
;         bf16x8 qf = *(const bf16x8*)(Qb + tok * 2048 + h * 256 + half * 128 + ks * 32 + fq * 8);
; #pragma unroll
;         for (int mt = 0; mt < 8; ++mt) {
;           bf16x8 kf = *(const bf16x8*)(Kb + (mt * 16 + fr) * 128 + ks * 32 + fq * 8);
;           sc[mt] = mfma16(kf, qf, sc[mt]);
;         }
;       }
	ds_read_b128 v[8:11], v224 offset:21952
	s_waitcnt vmcnt(0) lgkmcnt(0)
	v_mfma_f32_16x16x32_bf16 v[0:3], v[0:3], v[186:189], v[166:169]


; __device__ __forceinline__ f32x4 mfma16(bf16x8 a, bf16x8 b, f32x4 c) { return __builtin_amdgcn_mfma_f32_16x16x32_bf16(a, b, c, 0, 0, 0); }
; __device__ void ph_score(const P& p, int* lds) {
;     ...
;       for (int ks = 0; ks < 4; ++ks) {
;         bf16x8 qf = *(const bf16x8*)(Qb + tok * 2048 + h * 256 + half * 128 + ks * 32 + fq * 8);
; #pragma unroll
;         for (int mt = 0; mt < 8; ++mt) {
;           bf16x8 kf = *(const bf16x8*)(Kb + (mt * 16 + fr) * 128 + ks * 32 + fq * 8);
;           sc[mt] = mfma16(kf, qf, sc[mt]);
;         }
;       }
	s_nop 0
	ds_read_b128 v[170:173], v224 offset:30656
	s_waitcnt vmcnt(0) lgkmcnt(0)
	v_mfma_f32_16x16x32_bf16 v[166:169], v[8:11], v[186:189], v[174:177]


; __device__ __forceinline__ f32x4 mfma16(bf16x8 a, bf16x8 b, f32x4 c) { return __builtin_amdgcn_mfma_f32_16x16x32_bf16(a, b, c, 0, 0, 0); }
; __device__ void ph_score(const P& p, int* lds) {
;     ...
;       for (int ks = 0; ks < 4; ++ks) {
;         bf16x8 qf = *(const bf16x8*)(Qb + tok * 2048 + h * 256 + half * 128 + ks * 32 + fq * 8);
; #pragma unroll
;         for (int mt = 0; mt < 8; ++mt) {
;           bf16x8 kf = *(const bf16x8*)(Kb + (mt * 16 + fr) * 128 + ks * 32 + fq * 8);
;           sc[mt] = mfma16(kf, qf, sc[mt]);
;         }
;       }
;       int a[16], b[16];
; #pragma unroll
;       for (int mt = 0; mt < 4; ++mt)
; #pragma unroll
;         for (int r = 0; r < 4; ++r) {
;           a[mt * 4 + r] = key_pack(sc[mt][r], mt * 16 + fq * 4 + r, 0x7f);
;           b[mt * 4 + r] = key_pack(sc[mt + 4][r], (mt + 4) * 16 + fq * 4 + r, 0x7f);
;         }
	ds_read_b128 v[8:11], v224 offset:26304
	s_nop 0
	v_ashrrev_i32_e32 v174, 31, v190
	v_and_b32_e32 v174, 0x7fffffff, v174
	v_bitop3_b32 v48, v48, v174, v20 bitop3:0x36
	v_and_b32_e32 v174, 0xffffff80, v162
	v_ashrrev_i32_e32 v162, 31, v162
	v_and_b32_e32 v162, 0x7fffffff, v162
	v_ashrrev_i32_e32 v175, 31, v191
	v_bitop3_b32 v162, v174, v162, v56 bitop3:0x36
	v_and_b32_e32 v174, 0xffffff80, v191
	v_and_b32_e32 v175, 0x7fffffff, v175
	v_bitop3_b32 v174, v174, v175, v57 bitop3:0x36
	v_and_b32_e32 v175, 0xffffff80, v163
	v_ashrrev_i32_e32 v163, 31, v163
	v_and_b32_e32 v163, 0x7fffffff, v163
	v_ashrrev_i32_e32 v176, 31, v192
	v_bitop3_b32 v163, v175, v163, v58 bitop3:0x36
	v_and_b32_e32 v175, 0xffffff80, v192
	v_and_b32_e32 v176, 0x7fffffff, v176
	v_bitop3_b32 v175, v175, v176, v59 bitop3:0x36
	v_and_b32_e32 v176, 0xffffff80, v164
	v_ashrrev_i32_e32 v164, 31, v164
	v_and_b32_e32 v164, 0x7fffffff, v164
	v_ashrrev_i32_e32 v177, 31, v193
	v_bitop3_b32 v164, v176, v164, v60 bitop3:0x36
	v_and_b32_e32 v176, 0xffffff80, v193
	v_and_b32_e32 v177, 0x7fffffff, v177
	v_bitop3_b32 v176, v176, v177, v61 bitop3:0x36
	v_and_b32_e32 v177, 0xffffff80, v165
	v_ashrrev_i32_e32 v165, 31, v165
	v_and_b32_e32 v165, 0x7fffffff, v165
	v_bitop3_b32 v165, v177, v165, v62 bitop3:0x36
	v_and_b32_e32 v177, 0xffffff80, v12
	v_ashrrev_i32_e32 v12, 31, v12
	v_and_b32_e32 v12, 0x7fffffff, v12
	v_bitop3_b32 v12, v177, v12, v63 bitop3:0x36
	v_and_b32_e32 v177, 0xffffff80, v166
	v_ashrrev_i32_e32 v166, 31, v166
	v_and_b32_e32 v166, 0x7fffffff, v166
	v_bitop3_b32 v166, v177, v166, v64 bitop3:0x36
	v_and_b32_e32 v177, 0xffffff80, v13
	v_ashrrev_i32_e32 v13, 31, v13
	v_and_b32_e32 v13, 0x7fffffff, v13
	v_bitop3_b32 v13, v177, v13, v65 bitop3:0x36
	v_and_b32_e32 v177, 0xffffff80, v167
	v_ashrrev_i32_e32 v167, 31, v167
	v_and_b32_e32 v167, 0x7fffffff, v167
	v_bitop3_b32 v167, v177, v167, v66 bitop3:0x36
	v_and_b32_e32 v177, 0xffffff80, v14
	v_ashrrev_i32_e32 v14, 31, v14
	v_and_b32_e32 v14, 0x7fffffff, v14
	v_bitop3_b32 v14, v177, v14, v67 bitop3:0x36
	v_and_b32_e32 v177, 0xffffff80, v168
	v_ashrrev_i32_e32 v168, 31, v168
	v_and_b32_e32 v168, 0x7fffffff, v168
	v_bitop3_b32 v168, v177, v168, v68 bitop3:0x36
	v_and_b32_e32 v177, 0xffffff80, v15
	v_ashrrev_i32_e32 v15, 31, v15
	v_and_b32_e32 v15, 0x7fffffff, v15
	s_waitcnt vmcnt(0) lgkmcnt(0)
	v_mfma_f32_16x16x32_bf16 v[8:11], v[8:11], v[186:189], v[178:181]
	v_bitop3_b32 v15, v177, v15, v69 bitop3:0x36
	v_and_b32_e32 v177, 0xffffff80, v169
	v_ashrrev_i32_e32 v169, 31, v169
	v_and_b32_e32 v169, 0x7fffffff, v169
	v_bitop3_b32 v169, v177, v169, v70 bitop3:0x36
	v_and_b32_e32 v177, 0xffffff80, v4
	v_ashrrev_i32_e32 v4, 31, v4
	v_and_b32_e32 v4, 0x7fffffff, v4
	v_bitop3_b32 v4, v177, v4, v71 bitop3:0x36
	v_and_b32_e32 v177, 0xffffff80, v8
	v_ashrrev_i32_e32 v8, 31, v8
	v_and_b32_e32 v8, 0x7fffffff, v8
	v_bitop3_b32 v8, v177, v8, v72 bitop3:0x36
	v_and_b32_e32 v177, 0xffffff80, v5
	v_ashrrev_i32_e32 v5, 31, v5
	v_and_b32_e32 v5, 0x7fffffff, v5
	v_bitop3_b32 v5, v177, v5, v73 bitop3:0x36
	v_and_b32_e32 v177, 0xffffff80, v9
	v_ashrrev_i32_e32 v9, 31, v9
	v_and_b32_e32 v9, 0x7fffffff, v9
	v_bitop3_b32 v9, v177, v9, v74 bitop3:0x36
	v_and_b32_e32 v177, 0xffffff80, v6
	v_ashrrev_i32_e32 v6, 31, v6
	v_and_b32_e32 v6, 0x7fffffff, v6
	v_bitop3_b32 v6, v177, v6, v75 bitop3:0x36
	v_and_b32_e32 v177, 0xffffff80, v10
	v_ashrrev_i32_e32 v10, 31, v10
	v_and_b32_e32 v10, 0x7fffffff, v10
	v_bitop3_b32 v10, v177, v10, v76 bitop3:0x36
	v_and_b32_e32 v177, 0xffffff80, v7
	v_ashrrev_i32_e32 v7, 31, v7
	v_and_b32_e32 v7, 0x7fffffff, v7
	v_mfma_f32_16x16x32_bf16 v[170:173], v[170:173], v[186:189], v[182:185]
	v_bitop3_b32 v7, v177, v7, v77 bitop3:0x36
	v_and_b32_e32 v177, 0xffffff80, v11
	v_ashrrev_i32_e32 v11, 31, v11
	v_and_b32_e32 v11, 0x7fffffff, v11
	v_bitop3_b32 v11, v177, v11, v78 bitop3:0x36
	v_and_b32_e32 v177, 0xffffff80, v0
	v_ashrrev_i32_e32 v0, 31, v0
	v_and_b32_e32 v0, 0x7fffffff, v0
	v_bitop3_b32 v0, v177, v0, v79 bitop3:0x36
	v_and_b32_e32 v177, 0xffffff80, v170
	v_ashrrev_i32_e32 v170, 31, v170
	v_and_b32_e32 v170, 0x7fffffff, v170
	v_bitop3_b32 v170, v177, v170, v80 bitop3:0x36
	v_and_b32_e32 v177, 0xffffff80, v1
	v_ashrrev_i32_e32 v1, 31, v1
	v_and_b32_e32 v1, 0x7fffffff, v1
	v_bitop3_b32 v1, v177, v1, v81 bitop3:0x36
	v_and_b32_e32 v177, 0xffffff80, v171
	v_ashrrev_i32_e32 v171, 31, v171
	v_and_b32_e32 v171, 0x7fffffff, v171
	v_bitop3_b32 v171, v177, v171, v82 bitop3:0x36
	v_and_b32_e32 v177, 0xffffff80, v2
	v_ashrrev_i32_e32 v2, 31, v2
	v_and_b32_e32 v2, 0x7fffffff, v2
	v_bitop3_b32 v2, v177, v2, v83 bitop3:0x36
	v_and_b32_e32 v177, 0xffffff80, v172
	v_ashrrev_i32_e32 v172, 31, v172
	v_and_b32_e32 v172, 0x7fffffff, v172
	v_bitop3_b32 v172, v177, v172, v84 bitop3:0x36
	v_and_b32_e32 v177, 0xffffff80, v3
	v_ashrrev_i32_e32 v3, 31, v3
	v_and_b32_e32 v3, 0x7fffffff, v3
	v_bitop3_b32 v3, v177, v3, v85 bitop3:0x36
	v_and_b32_e32 v177, 0xffffff80, v173
	v_ashrrev_i32_e32 v173, 31, v173
	v_and_b32_e32 v173, 0x7fffffff, v173
	v_bitop3_b32 v173, v177, v173, v86 bitop3:0x36
	v_max_i32_e32 v177, v48, v174
	v_min_i32_e32 v48, v48, v174
	v_max_i32_e32 v174, v176, v175
	v_min_i32_e32 v175, v176, v175
	v_max_i32_e32 v176, v12, v13
	v_min_i32_e32 v12, v12, v13
	v_max_i32_e32 v13, v15, v14
	v_min_i32_e32 v14, v15, v14
	v_max_i32_e32 v15, v4, v5
	v_min_i32_e32 v4, v4, v5
	v_max_i32_e32 v5, v7, v6
	v_min_i32_e32 v6, v7, v6
	v_max_i32_e32 v7, v0, v1
	v_min_i32_e32 v0, v0, v1
	v_max_i32_e32 v1, v3, v2
	v_min_i32_e32 v2, v3, v2
	v_max_i32_e32 v3, v177, v175
	v_min_i32_e32 v175, v177, v175
	v_max_i32_e32 v177, v48, v174
	v_min_i32_e32 v48, v48, v174
; __device__ __forceinline__ void sort16p(int (&v)[16]) {
; #pragma unroll
;   for (int k = 2; k <= 16; k <<= 1)
; #pragma unroll
;     for (int j = k >> 1; j > 0; j >>= 1)
; #pragma unroll
;       for (int i = 0; i < 16; ++i) {
;         int l = i ^ j;
;         if (l > i) {
;           if ((i & k) == 0) { CE1(v[i], v[l]); }
;           else { CE1(v[l], v[i]); }
;         }
;       }
; }
	v_max_i32_e32 v174, v14, v176
	v_min_i32_e32 v14, v14, v176
	v_max_i32_e32 v176, v13, v12
	v_min_i32_e32 v12, v13, v12
	v_max_i32_e32 v13, v15, v6
	v_min_i32_e32 v6, v15, v6
	v_max_i32_e32 v15, v4, v5
	v_min_i32_e32 v4, v4, v5
	v_max_i32_e32 v5, v2, v7
	v_min_i32_e32 v2, v2, v7
	v_max_i32_e32 v7, v1, v0
	v_min_i32_e32 v0, v1, v0
	v_max_i32_e32 v1, v3, v177
	v_min_i32_e32 v3, v3, v177
	v_max_i32_e32 v177, v175, v48
	v_min_i32_e32 v48, v175, v48
	v_max_i32_e32 v175, v12, v14
	v_min_i32_e32 v12, v12, v14
	v_max_i32_e32 v14, v176, v174
	v_min_i32_e32 v174, v176, v174
	v_max_i32_e32 v176, v13, v15
	v_min_i32_e32 v13, v13, v15
	v_max_i32_e32 v15, v6, v4
	v_min_i32_e32 v4, v6, v4
	v_max_i32_e32 v6, v0, v2
	v_min_i32_e32 v0, v0, v2
	v_max_i32_e32 v2, v7, v5
	v_min_i32_e32 v5, v7, v5
	v_max_i32_e32 v7, v1, v12
	v_min_i32_e32 v1, v1, v12
	v_max_i32_e32 v12, v3, v175
	v_min_i32_e32 v3, v3, v175
	v_max_i32_e32 v175, v177, v174
	v_min_i32_e32 v174, v177, v174
	v_max_i32_e32 v177, v48, v14
	v_min_i32_e32 v14, v48, v14
	v_max_i32_e32 v48, v0, v176
	v_min_i32_e32 v0, v0, v176
	v_max_i32_e32 v176, v6, v13
	v_min_i32_e32 v6, v6, v13
	v_max_i32_e32 v13, v5, v15
	v_min_i32_e32 v5, v5, v15
	v_max_i32_e32 v15, v2, v4
	v_min_i32_e32 v2, v2, v4
	v_max_i32_e32 v4, v7, v175
	v_min_i32_e32 v7, v7, v175
	v_max_i32_e32 v175, v12, v177
	v_min_i32_e32 v12, v12, v177
	v_max_i32_e32 v177, v1, v174
	v_min_i32_e32 v1, v1, v174
	v_max_i32_e32 v174, v3, v14
	v_min_i32_e32 v3, v3, v14
	v_max_i32_e32 v14, v5, v0
	v_min_i32_e32 v0, v5, v0
	v_max_i32_e32 v5, v2, v6
	v_min_i32_e32 v2, v2, v6
	v_max_i32_e32 v6, v13, v48
	v_min_i32_e32 v13, v13, v48
	v_max_i32_e32 v48, v15, v176
	v_min_i32_e32 v15, v15, v176
	v_max_i32_e32 v176, v4, v175
	v_min_i32_e32 v4, v4, v175
	v_max_i32_e32 v175, v7, v12
	v_min_i32_e32 v7, v7, v12
	v_max_i32_e32 v12, v177, v174
	v_min_i32_e32 v174, v177, v174
	v_max_i32_e32 v177, v1, v3
	v_min_i32_e32 v1, v1, v3
	v_max_i32_e32 v3, v2, v0
	v_min_i32_e32 v0, v2, v0
	v_max_i32_e32 v2, v5, v14
	v_min_i32_e32 v5, v5, v14
	v_max_i32_e32 v14, v15, v13
	v_min_i32_e32 v13, v15, v13
	v_max_i32_e32 v15, v48, v6
	v_min_i32_e32 v6, v48, v6
	v_max_i32_e32 v48, v176, v0
	v_min_i32_e32 v0, v176, v0
	v_max_i32_e32 v176, v4, v3
	v_min_i32_e32 v3, v4, v3
	v_max_i32_e32 v4, v175, v5
	v_min_i32_e32 v5, v175, v5
	v_max_i32_e32 v175, v7, v2
	v_min_i32_e32 v2, v7, v2
	v_max_i32_e32 v7, v12, v13
	v_min_i32_e32 v12, v12, v13
	v_max_i32_e32 v13, v174, v14
	v_min_i32_e32 v14, v174, v14
	v_max_i32_e32 v174, v177, v6
	v_min_i32_e32 v6, v177, v6
	v_max_i32_e32 v177, v1, v15
	v_min_i32_e32 v1, v1, v15
	v_max_i32_e32 v15, v48, v7
	v_min_i32_e32 v7, v48, v7
	v_max_i32_e32 v48, v176, v13
	v_min_i32_e32 v13, v176, v13
	v_max_i32_e32 v176, v4, v174
	v_min_i32_e32 v4, v4, v174
	v_max_i32_e32 v174, v175, v177
	v_min_i32_e32 v175, v175, v177
	v_max_i32_e32 v177, v0, v12
	v_min_i32_e32 v0, v0, v12
	v_max_i32_e32 v12, v3, v14
	v_min_i32_e32 v3, v3, v14
	v_max_i32_e32 v14, v5, v6
	v_min_i32_e32 v5, v5, v6
	v_max_i32_e32 v6, v2, v1
	v_min_i32_e32 v1, v2, v1
	v_max_i32_e32 v2, v15, v176
	v_min_i32_e32 v15, v15, v176
	v_max_i32_e32 v176, v48, v174
	v_min_i32_e32 v48, v48, v174
	v_max_i32_e32 v174, v7, v4
	v_min_i32_e32 v4, v7, v4
	v_max_i32_e32 v7, v13, v175
	v_min_i32_e32 v13, v13, v175
	v_max_i32_e32 v175, v177, v14
	v_min_i32_e32 v14, v177, v14
	v_max_i32_e32 v177, v12, v6
	v_min_i32_e32 v6, v12, v6
	v_max_i32_e32 v12, v0, v5
	v_min_i32_e32 v0, v0, v5
	v_max_i32_e32 v5, v3, v1
	v_min_i32_e32 v1, v3, v1
	v_min_i32_e32 v3, v2, v176
	v_min_i32_e32 v178, v15, v48
	v_min_i32_e32 v179, v174, v7
	v_min_i32_e32 v180, v4, v13
	v_min_i32_e32 v181, v175, v177
	v_min_i32_e32 v182, v14, v6
	v_min_i32_e32 v183, v12, v5
	v_min_i32_e32 v184, v0, v1
	v_max_i32_e32 v185, v162, v163
	v_min_i32_e32 v162, v162, v163
	v_max_i32_e32 v163, v165, v164
	v_min_i32_e32 v164, v165, v164
	v_max_i32_e32 v165, v166, v167
	v_min_i32_e32 v166, v166, v167
	v_max_i32_e32 v167, v169, v168
	v_min_i32_e32 v168, v169, v168
	v_max_i32_e32 v169, v8, v9
	v_min_i32_e32 v8, v8, v9
	v_max_i32_e32 v9, v11, v10
	v_min_i32_e32 v10, v11, v10
	v_max_i32_e32 v11, v170, v171
	v_min_i32_e32 v170, v170, v171
	v_max_i32_e32 v171, v173, v172
	v_min_i32_e32 v172, v173, v172
	v_max_i32_e32 v173, v185, v164
	v_min_i32_e32 v164, v185, v164
	v_max_i32_e32 v185, v162, v163
	v_min_i32_e32 v162, v162, v163
	v_max_i32_e32 v163, v168, v165
	v_min_i32_e32 v165, v168, v165
	v_max_i32_e32 v168, v167, v166
	v_min_i32_e32 v166, v167, v166
	v_max_i32_e32 v167, v169, v10
	v_min_i32_e32 v10, v169, v10
	v_max_i32_e32 v169, v8, v9
	v_min_i32_e32 v8, v8, v9
	v_max_i32_e32 v9, v172, v11
	v_min_i32_e32 v11, v172, v11
	v_max_i32_e32 v172, v171, v170
	v_min_i32_e32 v170, v171, v170
	v_max_i32_e32 v171, v173, v185
	v_min_i32_e32 v173, v173, v185
	v_max_i32_e32 v185, v164, v162
	v_min_i32_e32 v162, v164, v162
	v_max_i32_e32 v164, v166, v165
	v_min_i32_e32 v165, v166, v165
	v_max_i32_e32 v166, v168, v163
	v_min_i32_e32 v163, v168, v163
	v_max_i32_e32 v168, v167, v169
	v_min_i32_e32 v167, v167, v169
	v_max_i32_e32 v169, v10, v8
	v_min_i32_e32 v8, v10, v8
	v_max_i32_e32 v10, v170, v11
	v_min_i32_e32 v11, v170, v11
	v_max_i32_e32 v170, v172, v9
	v_min_i32_e32 v9, v172, v9
	v_max_i32_e32 v172, v171, v165
	v_min_i32_e32 v165, v171, v165
	v_max_i32_e32 v171, v173, v164
	v_min_i32_e32 v164, v173, v164
	v_max_i32_e32 v173, v185, v163
	v_min_i32_e32 v163, v185, v163
	v_max_i32_e32 v185, v162, v166
	v_min_i32_e32 v162, v162, v166
	v_max_i32_e32 v166, v11, v168
	v_min_i32_e32 v11, v11, v168
	v_max_i32_e32 v168, v10, v167
	v_min_i32_e32 v10, v10, v167
	v_max_i32_e32 v167, v9, v169
; __device__ __forceinline__ void sort16p(int (&v)[16]) {
; #pragma unroll
;   for (int k = 2; k <= 16; k <<= 1)
; #pragma unroll
;     for (int j = k >> 1; j > 0; j >>= 1)
; #pragma unroll
;       for (int i = 0; i < 16; ++i) {
;         int l = i ^ j;
;         if (l > i) {
;           if ((i & k) == 0) { CE1(v[i], v[l]); }
;           else { CE1(v[l], v[i]); }
;         }
;       }
; }
; __device__ __forceinline__ void merge16p(int (&a)[16], const int (&b)[16]) {
; #pragma unroll
;   for (int i = 0; i < 16; ++i) a[i] = max(a[i], b[15 - i]);
; #pragma unroll
;   for (int j = 8; j > 0; j >>= 1)
; #pragma unroll
;     for (int i = 0; i < 16; ++i) {
;       int l = i ^ j;
;       if (l > i) { CE1(a[i], a[l]); }
;     }
; }
; __device__ __forceinline__ void xmerge16p(int (&a)[16], int mask) {
;   int b[16];
; #pragma unroll
;   for (int i = 0; i < 16; ++i) b[i] = (mask == 16) ? __builtin_amdgcn_ds_swizzle(a[i], 0x401F) : __shfl_xor(a[i], 32);
;   merge16p(a, b);
; }
	v_min_i32_e32 v9, v9, v169
	v_max_i32_e32 v169, v170, v8
	v_min_i32_e32 v8, v170, v8
	v_max_i32_e32 v170, v172, v173
	v_min_i32_e32 v172, v172, v173
	v_max_i32_e32 v173, v171, v185
	v_min_i32_e32 v171, v171, v185
	v_max_i32_e32 v185, v165, v163
	v_min_i32_e32 v163, v165, v163
	v_max_i32_e32 v165, v164, v162
	v_min_i32_e32 v162, v164, v162
	v_max_i32_e32 v164, v9, v11
	v_min_i32_e32 v9, v9, v11
	v_max_i32_e32 v11, v8, v10
	v_min_i32_e32 v8, v8, v10
	v_max_i32_e32 v10, v167, v166
	v_min_i32_e32 v166, v167, v166
	v_max_i32_e32 v167, v169, v168
	v_min_i32_e32 v168, v169, v168
	v_max_i32_e32 v169, v170, v173
	v_min_i32_e32 v170, v170, v173
	v_max_i32_e32 v173, v172, v171
	v_min_i32_e32 v171, v172, v171
	v_max_i32_e32 v172, v185, v165
	v_min_i32_e32 v165, v185, v165
	v_max_i32_e32 v185, v163, v162
	v_min_i32_e32 v162, v163, v162
	v_max_i32_e32 v163, v8, v9
	v_min_i32_e32 v8, v8, v9
	v_max_i32_e32 v9, v11, v164
	v_min_i32_e32 v11, v11, v164
	v_max_i32_e32 v164, v168, v166
	v_min_i32_e32 v166, v168, v166
	v_max_i32_e32 v168, v167, v10
	v_min_i32_e32 v10, v167, v10
	v_max_i32_e32 v167, v169, v8
	v_min_i32_e32 v8, v169, v8
	v_max_i32_e32 v169, v170, v163
	v_min_i32_e32 v163, v170, v163
	v_max_i32_e32 v170, v173, v11
	v_min_i32_e32 v11, v173, v11
	v_max_i32_e32 v173, v171, v9
	v_min_i32_e32 v9, v171, v9
	v_max_i32_e32 v171, v172, v166
	v_min_i32_e32 v166, v172, v166
	v_max_i32_e32 v172, v165, v164
	v_min_i32_e32 v164, v165, v164
	v_max_i32_e32 v165, v185, v10
	v_min_i32_e32 v10, v185, v10
	v_max_i32_e32 v185, v162, v168
	v_min_i32_e32 v162, v162, v168
	v_max_i32_e32 v168, v167, v171
	v_min_i32_e32 v167, v167, v171
	v_max_i32_e32 v171, v169, v172
	v_min_i32_e32 v169, v169, v172
	v_max_i32_e32 v172, v170, v165
	v_min_i32_e32 v165, v170, v165
	v_max_i32_e32 v170, v173, v185
	v_min_i32_e32 v173, v173, v185
	v_max_i32_e32 v185, v8, v166
	v_min_i32_e32 v8, v8, v166
	v_max_i32_e32 v166, v163, v164
	v_min_i32_e32 v163, v163, v164
	v_max_i32_e32 v164, v11, v10
	v_min_i32_e32 v10, v11, v10
	v_max_i32_e32 v11, v9, v162
	v_min_i32_e32 v9, v9, v162
	v_max_i32_e32 v162, v168, v172
	v_min_i32_e32 v168, v168, v172
	v_max_i32_e32 v172, v171, v170
	v_min_i32_e32 v170, v171, v170
	v_max_i32_e32 v171, v167, v165
	v_min_i32_e32 v165, v167, v165
	v_max_i32_e32 v167, v169, v173
	v_min_i32_e32 v169, v169, v173
	v_max_i32_e32 v173, v185, v164
	v_min_i32_e32 v164, v185, v164
	v_max_i32_e32 v185, v166, v11
	v_min_i32_e32 v11, v166, v11
	v_max_i32_e32 v166, v8, v10
	v_min_i32_e32 v8, v8, v10
	v_max_i32_e32 v10, v163, v9
	v_min_i32_e32 v9, v163, v9
	v_min_i32_e32 v163, v162, v172
	v_min_i32_e32 v186, v168, v170
	v_min_i32_e32 v187, v171, v167
	v_min_i32_e32 v188, v165, v169
	v_min_i32_e32 v189, v173, v185
	v_min_i32_e32 v190, v164, v11
	v_min_i32_e32 v191, v166, v10
	v_min_i32_e32 v192, v8, v9
	v_max3_i32 v2, v2, v176, v192
	v_max3_i32 v3, v3, v8, v9
	v_max3_i32 v8, v15, v48, v191
	v_max3_i32 v9, v178, v166, v10
	v_max3_i32 v7, v174, v7, v190
	v_max3_i32 v10, v179, v164, v11
	v_max3_i32 v4, v4, v13, v189
	v_max3_i32 v11, v180, v173, v185
	v_max3_i32 v13, v175, v177, v188
	v_max3_i32 v15, v181, v165, v169
	v_max3_i32 v6, v14, v6, v187
	v_max3_i32 v14, v182, v171, v167
	v_max3_i32 v5, v12, v5, v186
	v_max3_i32 v12, v183, v168, v170
	v_max3_i32 v0, v0, v1, v163
	v_max3_i32 v1, v184, v162, v172
	v_max_i32_e32 v48, v2, v13
	v_min_i32_e32 v2, v2, v13
	v_max_i32_e32 v13, v3, v15
	v_min_i32_e32 v3, v3, v15
	v_max_i32_e32 v15, v8, v6
	v_min_i32_e32 v6, v8, v6
	v_max_i32_e32 v8, v9, v14
	v_min_i32_e32 v9, v9, v14
	v_max_i32_e32 v14, v7, v5
	v_min_i32_e32 v5, v7, v5
	v_max_i32_e32 v7, v10, v12
	v_min_i32_e32 v10, v10, v12
	v_max_i32_e32 v12, v4, v0
	v_min_i32_e32 v0, v4, v0
	v_max_i32_e32 v4, v11, v1
	v_min_i32_e32 v1, v11, v1
	v_max_i32_e32 v11, v48, v14
	v_min_i32_e32 v14, v48, v14
	v_max_i32_e32 v48, v13, v7
	v_min_i32_e32 v7, v13, v7
	v_max_i32_e32 v13, v15, v12
	v_min_i32_e32 v12, v15, v12
	v_max_i32_e32 v15, v8, v4
	v_min_i32_e32 v4, v8, v4
	v_max_i32_e32 v8, v2, v5
	v_min_i32_e32 v2, v2, v5
	v_max_i32_e32 v5, v3, v10
	v_min_i32_e32 v3, v3, v10
	v_max_i32_e32 v10, v6, v0
	v_min_i32_e32 v0, v6, v0
	v_max_i32_e32 v6, v9, v1
	v_min_i32_e32 v1, v9, v1
	v_max_i32_e32 v9, v11, v13
	v_min_i32_e32 v11, v11, v13
	v_max_i32_e32 v13, v48, v15
	v_min_i32_e32 v15, v48, v15
	v_max_i32_e32 v48, v14, v12
	v_min_i32_e32 v12, v14, v12
	v_max_i32_e32 v14, v7, v4
	v_min_i32_e32 v4, v7, v4
	v_max_i32_e32 v7, v8, v10
	v_min_i32_e32 v8, v8, v10
	v_max_i32_e32 v10, v5, v6
	v_min_i32_e32 v5, v5, v6
	v_max_i32_e32 v6, v2, v0
	v_min_i32_e32 v0, v2, v0
	v_max_i32_e32 v2, v3, v1
	v_min_i32_e32 v1, v3, v1
	v_max_i32_e32 v3, v9, v13
	v_min_i32_e32 v9, v9, v13
	v_max_i32_e32 v13, v11, v15
	v_min_i32_e32 v11, v11, v15
	v_max_i32_e32 v15, v48, v14
	v_min_i32_e32 v14, v48, v14
	v_max_i32_e32 v48, v12, v4
	v_min_i32_e32 v4, v12, v4
	v_max_i32_e32 v12, v7, v10
	v_min_i32_e32 v7, v7, v10
	v_max_i32_e32 v10, v8, v5
	v_min_i32_e32 v5, v8, v5
	v_max_i32_e32 v8, v6, v2
	v_min_i32_e32 v2, v6, v2
	v_max_i32_e32 v6, v0, v1
	v_min_i32_e32 v0, v0, v1
	ds_swizzle_b32 v1, v3 offset:swizzle(SWAP,16)
	ds_swizzle_b32 v162, v9 offset:swizzle(SWAP,16)
	ds_swizzle_b32 v163, v13 offset:swizzle(SWAP,16)
	ds_swizzle_b32 v164, v11 offset:swizzle(SWAP,16)
	ds_swizzle_b32 v165, v15 offset:swizzle(SWAP,16)
	ds_swizzle_b32 v166, v14 offset:swizzle(SWAP,16)
	ds_swizzle_b32 v167, v48 offset:swizzle(SWAP,16)
	ds_swizzle_b32 v168, v4 offset:swizzle(SWAP,16)
	ds_swizzle_b32 v169, v12 offset:swizzle(SWAP,16)
	ds_swizzle_b32 v170, v7 offset:swizzle(SWAP,16)
	ds_swizzle_b32 v171, v10 offset:swizzle(SWAP,16)
	ds_swizzle_b32 v172, v0 offset:swizzle(SWAP,16)
	ds_swizzle_b32 v173, v6 offset:swizzle(SWAP,16)
	ds_swizzle_b32 v174, v2 offset:swizzle(SWAP,16)
	ds_swizzle_b32 v175, v8 offset:swizzle(SWAP,16)
	ds_swizzle_b32 v176, v5 offset:swizzle(SWAP,16)
	s_waitcnt lgkmcnt(4)
; __device__ __forceinline__ void merge16p(int (&a)[16], const int (&b)[16]) {
; #pragma unroll
;   for (int i = 0; i < 16; ++i) a[i] = max(a[i], b[15 - i]);
; #pragma unroll
;   for (int j = 8; j > 0; j >>= 1)
; #pragma unroll
;     for (int i = 0; i < 16; ++i) {
;       int l = i ^ j;
;       if (l > i) { CE1(a[i], a[l]); }
;     }
; }
; __device__ __forceinline__ void xmerge16p(int (&a)[16], int mask) {
;   int b[16];
; #pragma unroll
;   for (int i = 0; i < 16; ++i) b[i] = (mask == 16) ? __builtin_amdgcn_ds_swizzle(a[i], 0x401F) : __shfl_xor(a[i], 32);
;   merge16p(a, b);
; }
	v_max_i32_e32 v3, v3, v172
	s_waitcnt lgkmcnt(3)
	v_max_i32_e32 v9, v9, v173
	s_waitcnt lgkmcnt(2)
	v_max_i32_e32 v13, v13, v174
	s_waitcnt lgkmcnt(1)
	v_max_i32_e32 v11, v11, v175
	s_waitcnt lgkmcnt(0)
	v_max_i32_e32 v15, v15, v176
	v_max_i32_e32 v14, v14, v171
	v_max_i32_e32 v48, v48, v170
	v_max_i32_e32 v4, v4, v169
	v_max_i32_e32 v12, v12, v168
	v_max_i32_e32 v7, v7, v167
	v_max_i32_e32 v10, v10, v166
	v_max_i32_e32 v5, v5, v165
	v_max_i32_e32 v8, v8, v164
	v_max_i32_e32 v2, v2, v163
	v_max_i32_e32 v6, v6, v162
	v_max_i32_e32 v0, v0, v1
	v_max_i32_e32 v1, v3, v12
	v_min_i32_e32 v3, v3, v12
	v_max_i32_e32 v12, v9, v7
	v_min_i32_e32 v7, v9, v7
	v_max_i32_e32 v9, v13, v10
	v_min_i32_e32 v10, v13, v10
	v_max_i32_e32 v13, v11, v5
	v_min_i32_e32 v5, v11, v5
	v_max_i32_e32 v11, v15, v8
	v_min_i32_e32 v8, v15, v8
	v_max_i32_e32 v15, v14, v2
	v_min_i32_e32 v2, v14, v2
	v_max_i32_e32 v14, v48, v6
	v_min_i32_e32 v6, v48, v6
	v_max_i32_e32 v48, v4, v0
	v_min_i32_e32 v0, v4, v0
	v_max_i32_e32 v4, v1, v11
	v_min_i32_e32 v1, v1, v11
	v_max_i32_e32 v11, v12, v15
	v_min_i32_e32 v12, v12, v15
	v_max_i32_e32 v15, v9, v14
	v_min_i32_e32 v9, v9, v14
	v_max_i32_e32 v14, v13, v48
	v_min_i32_e32 v13, v13, v48
	v_max_i32_e32 v48, v3, v8
	v_min_i32_e32 v3, v3, v8
	v_max_i32_e32 v8, v7, v2
	v_min_i32_e32 v2, v7, v2
	v_max_i32_e32 v7, v10, v6
	v_min_i32_e32 v6, v10, v6
	v_max_i32_e32 v10, v5, v0
	v_min_i32_e32 v0, v5, v0
	v_max_i32_e32 v5, v4, v15
	v_min_i32_e32 v4, v4, v15
	v_max_i32_e32 v15, v11, v14
	v_min_i32_e32 v11, v11, v14
	v_max_i32_e32 v14, v1, v9
	v_min_i32_e32 v1, v1, v9
	v_max_i32_e32 v9, v12, v13
	v_min_i32_e32 v12, v12, v13
	v_max_i32_e32 v13, v48, v7
	v_min_i32_e32 v7, v48, v7
	v_max_i32_e32 v48, v8, v10
	v_min_i32_e32 v8, v8, v10
	v_max_i32_e32 v10, v3, v6
	v_min_i32_e32 v3, v3, v6
	v_max_i32_e32 v6, v2, v0
	v_min_i32_e32 v0, v2, v0
	v_max_i32_e32 v2, v5, v15
	v_min_i32_e32 v5, v5, v15
	v_max_i32_e32 v15, v4, v11
	v_min_i32_e32 v4, v4, v11
	v_max_i32_e32 v11, v14, v9
	v_min_i32_e32 v9, v14, v9
	v_max_i32_e32 v14, v1, v12
	v_min_i32_e32 v1, v1, v12
	v_max_i32_e32 v12, v13, v48
	v_min_i32_e32 v13, v13, v48
	v_max_i32_e32 v48, v7, v8
	v_min_i32_e32 v7, v7, v8
	v_max_i32_e32 v8, v10, v6
	v_min_i32_e32 v6, v10, v6
	v_max_i32_e32 v10, v3, v0
	v_min_i32_e32 v0, v3, v0
	ds_bpermute_b32 v3, v54, v2
	ds_bpermute_b32 v162, v54, v5
	ds_bpermute_b32 v163, v54, v15
	ds_bpermute_b32 v164, v54, v4
	ds_bpermute_b32 v165, v54, v11
	ds_bpermute_b32 v166, v54, v9
	ds_bpermute_b32 v167, v54, v14
	ds_bpermute_b32 v168, v54, v1
	ds_bpermute_b32 v169, v54, v12
	ds_bpermute_b32 v170, v54, v13
	ds_bpermute_b32 v171, v54, v48
	ds_bpermute_b32 v172, v54, v0
	ds_bpermute_b32 v173, v54, v10
	ds_bpermute_b32 v174, v54, v6
	ds_bpermute_b32 v175, v54, v8
	ds_bpermute_b32 v176, v54, v7
	s_waitcnt lgkmcnt(4)
	v_max_i32_e32 v2, v2, v172
	s_waitcnt lgkmcnt(3)
	v_max_i32_e32 v5, v5, v173
	s_waitcnt lgkmcnt(2)
	v_max_i32_e32 v15, v15, v174
	s_waitcnt lgkmcnt(1)
	v_max_i32_e32 v4, v4, v175
	s_waitcnt lgkmcnt(0)
; __device__ __forceinline__ void merge16p(int (&a)[16], const int (&b)[16]) {
; #pragma unroll
;   for (int i = 0; i < 16; ++i) a[i] = max(a[i], b[15 - i]);
; #pragma unroll
;   for (int j = 8; j > 0; j >>= 1)
; #pragma unroll
;     for (int i = 0; i < 16; ++i) {
;       int l = i ^ j;
;       if (l > i) { CE1(a[i], a[l]); }
;     }
; }
; __device__ void ph_score(const P& p, int* lds) {
;     ...
;       int idx4[4];
; #pragma unroll
;       for (int i = 0; i < 16; ++i) {
;         const int k = key_unmap(a[i]);
;         tv[half][i] = __int_as_float(k & ~0x7f);
;         if ((i >> 2) == 0) idx4[i & 3] = k & 0x7f;
;       }
; #pragma unroll
;       for (int i = 4; i < 16; ++i) {
;         const int k = key_unmap(a[i]) & 0x7f;
;         if ((i >> 2) == 1) idx4[i & 3] = (fq == 1) ? k : idx4[i & 3];
;         if ((i >> 2) == 2) idx4[i & 3] = (fq == 2) ? k : idx4[i & 3];
;         if ((i >> 2) == 3) idx4[i & 3] = (fq == 3) ? k : idx4[i & 3];
;       }
;       *(int4*)(myl + half * 16 + fq * 4) = make_int4(idx4[0], idx4[1], idx4[2], idx4[3]);
	v_max_i32_e32 v11, v11, v176
	v_max_i32_e32 v9, v9, v171
	v_max_i32_e32 v14, v14, v170
	v_max_i32_e32 v1, v1, v169
	v_max_i32_e32 v12, v12, v168
	v_max_i32_e32 v13, v13, v167
	v_max_i32_e32 v48, v48, v166
	v_max_i32_e32 v7, v7, v165
	v_max_i32_e32 v8, v8, v164
	v_max_i32_e32 v6, v6, v163
	v_max_i32_e32 v10, v10, v162
	v_max_i32_e32 v0, v0, v3
	v_max_i32_e32 v3, v2, v12
	v_min_i32_e32 v2, v2, v12
	v_max_i32_e32 v12, v5, v13
	v_min_i32_e32 v5, v5, v13
	v_max_i32_e32 v13, v15, v48
	v_min_i32_e32 v15, v15, v48
	v_max_i32_e32 v48, v4, v7
	v_min_i32_e32 v4, v4, v7
	v_max_i32_e32 v7, v11, v8
	v_min_i32_e32 v8, v11, v8
	v_max_i32_e32 v11, v9, v6
	v_min_i32_e32 v6, v9, v6
	v_max_i32_e32 v9, v14, v10
	v_min_i32_e32 v10, v14, v10
	v_max_i32_e32 v14, v1, v0
	v_min_i32_e32 v0, v1, v0
	v_max_i32_e32 v1, v3, v7
	v_min_i32_e32 v3, v3, v7
	v_max_i32_e32 v7, v12, v11
	v_min_i32_e32 v11, v12, v11
	v_max_i32_e32 v12, v13, v9
	v_min_i32_e32 v9, v13, v9
	v_max_i32_e32 v13, v48, v14
	v_min_i32_e32 v14, v48, v14
	v_max_i32_e32 v48, v2, v8
	v_min_i32_e32 v2, v2, v8
	v_max_i32_e32 v8, v5, v6
	v_min_i32_e32 v5, v5, v6
	v_max_i32_e32 v6, v15, v10
	v_min_i32_e32 v10, v15, v10
	v_max_i32_e32 v15, v4, v0
	v_min_i32_e32 v0, v4, v0
	v_max_i32_e32 v4, v1, v12
	v_min_i32_e32 v1, v1, v12
	v_max_i32_e32 v12, v7, v13
	v_min_i32_e32 v7, v7, v13
	v_max_i32_e32 v13, v3, v9
	v_min_i32_e32 v3, v3, v9
	v_max_i32_e32 v9, v11, v14
	v_min_i32_e32 v11, v11, v14
	v_max_i32_e32 v14, v48, v6
	v_min_i32_e32 v48, v48, v6
	v_max_i32_e32 v6, v8, v15
	v_min_i32_e32 v8, v8, v15
	v_max_i32_e32 v162, v2, v10
	v_min_i32_e32 v2, v2, v10
	v_max_i32_e32 v163, v5, v0
	v_min_i32_e32 v0, v5, v0
	v_max_i32_e32 v165, v4, v12
	v_min_i32_e32 v12, v4, v12
	v_max_i32_e32 v166, v1, v7
	v_min_i32_e32 v167, v1, v7
	v_max_i32_e32 v4, v13, v9
	v_min_i32_e32 v5, v13, v9
	v_max_i32_e32 v10, v3, v11
	v_min_i32_e32 v3, v3, v11
	v_max_i32_e32 v15, v14, v6
	v_min_i32_e32 v14, v14, v6
	v_max_i32_e32 v6, v48, v8
	v_min_i32_e32 v1, v48, v8
	v_max_i32_e32 v164, v162, v163
	v_min_i32_e32 v163, v162, v163
	v_max_i32_e32 v162, v2, v0
	v_min_i32_e32 v9, v2, v0
	v_ashrrev_i32_e32 v0, 31, v165
	v_and_b32_e32 v7, 0x7fffffff, v0
	v_bitop3_b32 v2, v0, v165, s75 bitop3:0x6c
	v_bitop3_b32 v0, v7, s80, v165 bitop3:0x48
	v_ashrrev_i32_e32 v165, 31, v4
	v_ashrrev_i32_e32 v7, 31, v12
	v_bitop3_b32 v165, v165, s80, v4 bitop3:0x48
	v_and_b32_e32 v8, 0x7fffffff, v7
	v_cndmask_b32_e64 v0, v0, v165, s[6:7]
	v_ashrrev_i32_e32 v165, 31, v5
	v_bitop3_b32 v8, v8, s80, v12 bitop3:0x48
	v_ashrrev_i32_e32 v11, 31, v166
	v_bitop3_b32 v165, v165, s80, v5 bitop3:0x48
	v_and_b32_e32 v13, 0x7fffffff, v11
	v_cndmask_b32_e64 v8, v8, v165, s[6:7]
	v_ashrrev_i32_e32 v165, 31, v10
	v_bitop3_b32 v7, v7, v12, s75 bitop3:0x6c
	v_bitop3_b32 v12, v11, v166, s75 bitop3:0x6c
	v_bitop3_b32 v11, v13, s80, v166 bitop3:0x48
	v_ashrrev_i32_e32 v13, 31, v167
	v_bitop3_b32 v165, v165, s80, v10 bitop3:0x48
	v_and_b32_e32 v48, 0x7fffffff, v13
	v_cndmask_b32_e64 v11, v11, v165, s[6:7]
	v_ashrrev_i32_e32 v165, 31, v3
	v_bitop3_b32 v48, v48, s80, v167 bitop3:0x48
	v_bitop3_b32 v165, v165, s80, v3 bitop3:0x48
	v_cndmask_b32_e64 v48, v48, v165, s[6:7]
	v_ashrrev_i32_e32 v165, 31, v15
	v_bitop3_b32 v165, v165, s80, v15 bitop3:0x48
	v_cndmask_b32_e64 v0, v0, v165, s[4:5]
	v_ashrrev_i32_e32 v165, 31, v14
	v_bitop3_b32 v165, v165, s80, v14 bitop3:0x48
	v_cndmask_b32_e64 v8, v8, v165, s[4:5]
	v_ashrrev_i32_e32 v165, 31, v6
	v_bitop3_b32 v165, v165, s80, v6 bitop3:0x48
	v_cndmask_b32_e64 v11, v11, v165, s[4:5]
	v_ashrrev_i32_e32 v165, 31, v1
	v_bitop3_b32 v165, v165, s80, v1 bitop3:0x48
	v_cndmask_b32_e64 v48, v48, v165, s[4:5]
	v_ashrrev_i32_e32 v165, 31, v164
	v_bitop3_b32 v165, v165, s80, v164 bitop3:0x48
	v_cndmask_b32_e64 v166, v0, v165, s[0:1]
	v_ashrrev_i32_e32 v0, 31, v163
	v_bitop3_b32 v0, v0, s80, v163 bitop3:0x48
	v_bitop3_b32 v13, v13, v167, s75 bitop3:0x6c
	v_cndmask_b32_e64 v167, v8, v0, s[0:1]
	v_ashrrev_i32_e32 v0, 31, v162
	v_bitop3_b32 v0, v0, s80, v162 bitop3:0x48
	v_cndmask_b32_e64 v168, v11, v0, s[0:1]
	v_ashrrev_i32_e32 v0, 31, v9
	v_bitop3_b32 v0, v0, s80, v9 bitop3:0x48
	v_cmp_gt_i32_e64 s[54:55], 0, v5
	v_cmp_gt_i32_e64 s[56:57], 0, v4
	v_cmp_gt_i32_e64 s[50:51], 0, v3
	v_cmp_gt_i32_e64 s[52:53], 0, v10
	v_cmp_gt_i32_e64 s[48:49], 0, v15
	v_cmp_gt_i32_e64 s[42:43], 0, v14
	v_cmp_gt_i32_e64 s[44:45], 0, v1
	v_cmp_gt_i32_e64 s[46:47], 0, v6
	v_cmp_gt_i32_e64 s[40:41], 0, v164
	v_cmp_gt_i32_e64 s[38:39], 0, v163
	v_cmp_gt_i32_e64 s[36:37], 0, v162
	v_cmp_gt_i32_e64 s[34:35], 0, v9
	v_cndmask_b32_e64 v169, v48, v0, s[0:1]
	v_cmp_lt_i32_e64 s[58:59], 1, v21
	ds_write_b128 v150, v[166:169] offset:64
	s_and_saveexec_b64 s[62:63], s[58:59]
	s_xor_b64 s[78:79], exec, s[62:63]
	s_cbranch_execz .LBB0_764
	v_cmp_lt_i32_e64 s[58:59], 2, v21
	s_and_saveexec_b64 s[62:63], s[58:59]
	s_xor_b64 s[58:59], exec, s[62:63]
	v_cndmask_b32_e64 v0, 0, v151, s[30:31]
	v_bitop3_b32 v48, v0, v160, s33 bitop3:0x78
	s_andn2_saveexec_b64 s[30:31], s[58:59]
	v_cndmask_b32_e64 v0, 0, v151, s[28:29]
	v_bitop3_b32 v48, v0, v159, s33 bitop3:0x78
	s_or_b64 exec, exec, s[30:31]
